# opt44: opt41 + early K-fragment reads in the diff-attention loop + nt hint on the large bf16 epilogue stores (G1, G3/G4, G7)
# speedup vs baseline: 1.0031x; 1.0031x over previous
; __device__ __forceinline__ unsigned cvt_pk_bf16(float lo, float hi) { f32x2_t v = {lo, hi}; bf16x2_t b = __builtin_convertvector(v, bf16x2_t); return __builtin_bit_cast(unsigned, b); }
; __device__ __forceinline__ float rstd_of(const float* ss, int row) { return __builtin_amdgcn_rsqf(ss[row] * (1.0f / 1024.0f) + RMS_EPS); }
; __device__ __forceinline__ float sigmoidf_(float v) { return __builtin_amdgcn_rcpf(1.0f + __builtin_amdgcn_exp2f(-v * LOG2E)); }
;     __device__ __forceinline__ void operator()(const Acc& acc, const Unit& u, int wr, int wc, int fr, int fq) const {
;     ...
;                 const int row = row0 + ai * HALF + m * 16; const float rs = rstd_of(ss, row) * sc;
;                 const int b = row >> 11, t = row & (SEQ - 1);
; #pragma unroll
;                 for (int bj = 0; bj < 2; ++bj) {
;                     float o[8];
; #pragma unroll
;                     for (int n = 0; n < 2; ++n)
; #pragma unroll
;                         for (int e = 0; e < 4; ++e) { float v = acc[ai][bj][m][n][e] * rs; if (isg) v = sigmoidf_(v + bv[bj][4 * n + e]); o[4 * n + e] = v; }
;                     u32x4 w; w.x = cvt_pk_bf16(o[0], o[1]); w.y = cvt_pk_bf16(o[2], o[3]); w.z = cvt_pk_bf16(o[4], o[5]); w.w = cvt_pk_bf16(o[6], o[7]);
;                     bf16_t* dst;
;                     if (tile < 4) dst = P + (size_t)row * PP + C_DQ + tile * BM + bj * HALF + cc;
;                     else if (tile < 8) dst = KD + ((size_t)((b * 8 + (tile - 4) * 2 + bj) * SEQ + t)) * 128 + cc;
;                     else if (tile < 12) dst = P + (size_t)row * PP + C_SQ + (tile - 8) * BM + bj * HALF + cc;
;                     else if (tile == 12) { const int ccf = bj * HALF + cc; dst = KS + ((size_t)((b * 4 + (ccf >> 6)) * SEQ + t)) * 64 + (ccf & 63); }
;                     else dst = P + (size_t)row * PP + C_GA + (tile - 13) * BM + bj * HALF + cc;
;                     *(u32x4*)dst = w;
.LBB0_450:
	s_and_b32 s6, s14, 0x7ffffffc
	s_waitcnt vmcnt(0)
	v_fmamk_f32 v157, v220, 0x3a800000, v170
	s_cmp_eq_u32 s6, 8
	v_rsq_f32_e32 v157, v157
	s_cselect_b64 s[6:7], -1, 0
	s_or_b64 vcc, s[96:97], s[6:7]
	v_cndmask_b32_e32 v153, 1.0, v173, vcc
	v_mul_f32_e32 v157, v153, v157
	v_mul_f32_e32 v179, v124, v157
	v_fma_f32 v124, v124, v157, v187
	v_mul_f32_e32 v124, 0xbfb8aa3b, v124
	v_exp_f32_e32 v124, v124
	v_readlane_b32 s70, v254, 54
	s_mov_b64 s[6:7], -1
	s_andn2_b64 vcc, exec, s[12:13]
	v_add_f32_e32 v124, 1.0, v124
	v_rcp_f32_e32 v124, v124
	v_readlane_b32 s69, v254, 53
	v_readlane_b32 s71, v254, 55
	v_cndmask_b32_e64 v124, v179, v124, s[10:11]
	v_mul_f32_e32 v179, v125, v157
	v_fma_f32 v125, v125, v157, v186
	v_mul_f32_e32 v125, 0xbfb8aa3b, v125
	v_exp_f32_e32 v125, v125
	s_nop 0
	v_add_f32_e32 v125, 1.0, v125
	v_rcp_f32_e32 v125, v125
	s_nop 0
	v_cndmask_b32_e64 v125, v179, v125, s[10:11]
	v_mul_f32_e32 v179, v126, v157
	v_fma_f32 v126, v126, v157, v191
	v_mul_f32_e32 v126, 0xbfb8aa3b, v126
	v_exp_f32_e32 v126, v126
	s_nop 0
	v_add_f32_e32 v126, 1.0, v126
	v_rcp_f32_e32 v126, v126
	s_nop 0
	v_cndmask_b32_e64 v126, v179, v126, s[10:11]
	v_mul_f32_e32 v179, v127, v157
	v_fma_f32 v127, v127, v157, v188
	v_mul_f32_e32 v127, 0xbfb8aa3b, v127
	v_exp_f32_e32 v127, v127
	s_nop 0
	v_add_f32_e32 v127, 1.0, v127
	v_rcp_f32_e32 v127, v127
	s_nop 0
	v_cndmask_b32_e64 v127, v179, v127, s[10:11]
	v_mul_f32_e32 v179, v120, v157
	v_fma_f32 v120, v120, v157, v192
	v_mul_f32_e32 v120, 0xbfb8aa3b, v120
	v_exp_f32_e32 v120, v120
	s_nop 0
	v_add_f32_e32 v120, 1.0, v120
	v_rcp_f32_e32 v120, v120
	s_nop 0
	v_cndmask_b32_e64 v179, v179, v120, s[10:11]
	v_mul_f32_e32 v120, v121, v157
	v_fma_f32 v121, v121, v157, v189
	v_mul_f32_e32 v121, 0xbfb8aa3b, v121
	v_exp_f32_e32 v121, v121
	s_nop 0
	v_add_f32_e32 v121, 1.0, v121
	v_rcp_f32_e32 v121, v121
	s_nop 0
	v_cndmask_b32_e64 v195, v120, v121, s[10:11]
	v_fma_f32 v121, v122, v157, v193
	v_mul_f32_e32 v121, 0xbfb8aa3b, v121
	v_exp_f32_e32 v121, v121
	v_mul_f32_e32 v120, v122, v157
	v_cvt_pk_bf16_f32 v122, v179, v195
	v_add_f32_e32 v121, 1.0, v121
	v_rcp_f32_e32 v121, v121
	s_nop 0
	v_cndmask_b32_e64 v196, v120, v121, s[10:11]
	v_fma_f32 v121, v123, v157, v190
	v_mul_f32_e32 v121, 0xbfb8aa3b, v121
	v_exp_f32_e32 v121, v121
	v_mul_f32_e32 v120, v123, v157
	v_add_f32_e32 v121, 1.0, v121
	v_rcp_f32_e32 v121, v121
	s_nop 0
	v_cndmask_b32_e64 v123, v120, v121, s[10:11]
	v_cvt_pk_bf16_f32 v120, v124, v125
	v_cvt_pk_bf16_f32 v121, v126, v127
	v_cvt_pk_bf16_f32 v123, v196, v123
	global_store_dwordx4 v[164:165], v[120:123], off nt
	s_nop 1
	v_cndmask_b32_e64 v120, 0, 1, s[12:13]
	v_cmp_ne_u32_e64 s[14:15], 1, v120
	v_cndmask_b32_e64 v120, 0, 1, s[94:95]
	v_cmp_ne_u32_e64 s[12:13], 1, v120
	s_cbranch_vccnz .LBB0_464
	s_and_b64 vcc, exec, s[12:13]
	s_cbranch_vccnz .LBB0_461
	s_andn2_b64 vcc, exec, s[90:91]
	s_cbranch_vccnz .LBB0_458
	s_andn2_b64 vcc, exec, s[88:89]
	s_cbranch_vccnz .LBB0_455
	v_lshl_add_u64 v[120:121], s[0:1], 1, v[162:163]
	v_lshl_add_u64 v[120:121], v[120:121], 0, v[136:137]
	v_lshl_add_u64 v[120:121], v[120:121], 0, s[36:37]
	s_mov_b64 s[6:7], 0

; __device__ __forceinline__ unsigned cvt_pk_bf16(float lo, float hi) { f32x2_t v = {lo, hi}; bf16x2_t b = __builtin_convertvector(v, bf16x2_t); return __builtin_bit_cast(unsigned, b); }
; __device__ __forceinline__ float sigmoidf_(float v) { return __builtin_amdgcn_rcpf(1.0f + __builtin_amdgcn_exp2f(-v * LOG2E)); }
;     __device__ __forceinline__ void operator()(const Acc& acc, const Unit& u, int wr, int wc, int fr, int fq) const {
;     ...
;                 const int b = row >> 11, t = row & (SEQ - 1);
; #pragma unroll
;                 for (int bj = 0; bj < 2; ++bj) {
;                     float o[8];
; #pragma unroll
;                     for (int n = 0; n < 2; ++n)
; #pragma unroll
;                         for (int e = 0; e < 4; ++e) { float v = acc[ai][bj][m][n][e] * rs; if (isg) v = sigmoidf_(v + bv[bj][4 * n + e]); o[4 * n + e] = v; }
;                     u32x4 w; w.x = cvt_pk_bf16(o[0], o[1]); w.y = cvt_pk_bf16(o[2], o[3]); w.z = cvt_pk_bf16(o[4], o[5]); w.w = cvt_pk_bf16(o[6], o[7]);
;                     bf16_t* dst;
;                     if (tile < 4) dst = P + (size_t)row * PP + C_DQ + tile * BM + bj * HALF + cc;
;                     else if (tile < 8) dst = KD + ((size_t)((b * 8 + (tile - 4) * 2 + bj) * SEQ + t)) * 128 + cc;
;                     else if (tile < 12) dst = P + (size_t)row * PP + C_SQ + (tile - 8) * BM + bj * HALF + cc;
;                     else if (tile == 12) { const int ccf = bj * HALF + cc; dst = KS + ((size_t)((b * 4 + (ccf >> 6)) * SEQ + t)) * 64 + (ccf & 63); }
;                     else dst = P + (size_t)row * PP + C_GA + (tile - 13) * BM + bj * HALF + cc;
;                     *(u32x4*)dst = w;
.LBB0_466:
	v_mul_f32_e32 v122, v116, v157
	v_fma_f32 v116, v116, v157, v181
	v_mul_f32_e32 v116, 0xbfb8aa3b, v116
	v_exp_f32_e32 v116, v116
	s_movk_i32 s6, 0x7df
	s_mov_b64 s[94:95], -1
	s_and_b64 vcc, exec, s[14:15]
	v_add_f32_e32 v116, 1.0, v116
	v_rcp_f32_e32 v116, v116
	s_nop 0
	v_cndmask_b32_e64 v116, v122, v116, s[10:11]
	v_mul_f32_e32 v122, v117, v157
	v_fma_f32 v117, v117, v157, v174
	v_mul_f32_e32 v117, 0xbfb8aa3b, v117
	v_exp_f32_e32 v117, v117
	s_nop 0
	v_add_f32_e32 v117, 1.0, v117
	v_rcp_f32_e32 v117, v117
	s_nop 0
	v_cndmask_b32_e64 v117, v122, v117, s[10:11]
	v_mul_f32_e32 v122, v118, v157
	v_fma_f32 v118, v118, v157, v183
	v_mul_f32_e32 v118, 0xbfb8aa3b, v118
	v_exp_f32_e32 v118, v118
	s_nop 0
	v_add_f32_e32 v118, 1.0, v118
	v_rcp_f32_e32 v118, v118
	s_nop 0
	v_cndmask_b32_e64 v118, v122, v118, s[10:11]
	v_mul_f32_e32 v122, v119, v157
	v_fma_f32 v119, v119, v157, v178
	v_mul_f32_e32 v119, 0xbfb8aa3b, v119
	v_exp_f32_e32 v119, v119
	s_nop 0
	v_add_f32_e32 v119, 1.0, v119
	v_rcp_f32_e32 v119, v119
	s_nop 0
	v_cndmask_b32_e64 v119, v122, v119, s[10:11]
	v_mul_f32_e32 v122, v112, v157
	v_fma_f32 v112, v112, v157, v184
	v_mul_f32_e32 v112, 0xbfb8aa3b, v112
	v_exp_f32_e32 v112, v112
	s_nop 0
	v_add_f32_e32 v112, 1.0, v112
	v_rcp_f32_e32 v112, v112
	s_nop 0
	v_cndmask_b32_e64 v122, v122, v112, s[10:11]
	v_mul_f32_e32 v112, v113, v157
	v_fma_f32 v113, v113, v157, v180
	v_mul_f32_e32 v113, 0xbfb8aa3b, v113
	v_exp_f32_e32 v113, v113
	s_nop 0
	v_add_f32_e32 v113, 1.0, v113
	v_rcp_f32_e32 v113, v113
	s_nop 0
	v_cndmask_b32_e64 v123, v112, v113, s[10:11]
	v_fma_f32 v113, v114, v157, v185
	v_mul_f32_e32 v113, 0xbfb8aa3b, v113
	v_exp_f32_e32 v113, v113
	v_mul_f32_e32 v112, v114, v157
	v_cvt_pk_bf16_f32 v114, v122, v123
	v_add_f32_e32 v113, 1.0, v113
	v_rcp_f32_e32 v113, v113
	s_nop 0
	v_cndmask_b32_e64 v124, v112, v113, s[10:11]
	v_fma_f32 v113, v115, v157, v182
	v_mul_f32_e32 v113, 0xbfb8aa3b, v113
	v_exp_f32_e32 v113, v113
	v_mul_f32_e32 v112, v115, v157
	v_add_f32_e32 v113, 1.0, v113
	v_rcp_f32_e32 v113, v113
	s_nop 0
	v_cndmask_b32_e64 v115, v112, v113, s[10:11]
	v_cvt_pk_bf16_f32 v112, v116, v117
	v_cvt_pk_bf16_f32 v113, v118, v119
	v_cvt_pk_bf16_f32 v115, v124, v115
	global_store_dwordx4 v[120:121], v[112:115], off nt
	v_bitop3_b32 v120, v152, s6, 16 bitop3:0xc8
	s_nop 0
	v_or_b32_e32 v112, 16, v152
	v_ashrrev_i32_e32 v113, 31, v112
	v_lshl_add_u64 v[114:115], v[112:113], 2, s[44:45]
	s_nop 0
	v_lshlrev_b64 v[114:115], 13, v[112:113]
	v_or_b32_e32 v112, s17, v120
	s_cbranch_vccnz .LBB0_480
	s_and_b64 vcc, exec, s[12:13]
	s_mov_b64 s[6:7], -1
	s_cbranch_vccnz .LBB0_477
	s_andn2_b64 vcc, exec, s[90:91]
	s_cbranch_vccnz .LBB0_474
	s_andn2_b64 vcc, exec, s[88:89]
	s_cbranch_vccnz .LBB0_471
	v_lshl_add_u64 v[116:117], s[20:21], 0, v[114:115]
	v_lshl_add_u64 v[116:117], s[0:1], 1, v[116:117]
	v_lshl_add_u64 v[116:117], v[116:117], 0, v[136:137]
	v_lshl_add_u64 v[118:119], v[116:117], 0, s[30:31]
	s_mov_b64 s[6:7], 0

;     __device__ __forceinline__ void operator()(const Acc& acc, const Unit& u, int wr, int wc, int fr, int fq) const {
;     ...
;                     bf16_t* dst;
;                     if (tile < 4) dst = P + (size_t)row * PP + C_DQ + tile * BM + bj * HALF + cc;
;                     else if (tile < 8) dst = KD + ((size_t)((b * 8 + (tile - 4) * 2 + bj) * SEQ + t)) * 128 + cc;
;                     else if (tile < 12) dst = P + (size_t)row * PP + C_SQ + (tile - 8) * BM + bj * HALF + cc;
;                     else if (tile == 12) { const int ccf = bj * HALF + cc; dst = KS + ((size_t)((b * 4 + (ccf >> 6)) * SEQ + t)) * 64 + (ccf & 63); }
;                     else dst = P + (size_t)row * PP + C_GA + (tile - 13) * BM + bj * HALF + cc;
;                     *(u32x4*)dst = w;
.LBB0_482:

; __device__ __forceinline__ unsigned cvt_pk_bf16(float lo, float hi) { f32x2_t v = {lo, hi}; bf16x2_t b = __builtin_convertvector(v, bf16x2_t); return __builtin_bit_cast(unsigned, b); }
; __device__ __forceinline__ float rstd_of(const float* ss, int row) { return __builtin_amdgcn_rsqf(ss[row] * (1.0f / 1024.0f) + RMS_EPS); }
; __device__ __forceinline__ float sigmoidf_(float v) { return __builtin_amdgcn_rcpf(1.0f + __builtin_amdgcn_exp2f(-v * LOG2E)); }
;     __device__ __forceinline__ void operator()(const Acc& acc, const Unit& u, int wr, int wc, int fr, int fq) const {
;     ...
;                 const int row = row0 + ai * HALF + m * 16; const float rs = rstd_of(ss, row) * sc;
;                 const int b = row >> 11, t = row & (SEQ - 1);
; #pragma unroll
;                 for (int bj = 0; bj < 2; ++bj) {
;                     float o[8];
; #pragma unroll
;                     for (int n = 0; n < 2; ++n)
; #pragma unroll
;                         for (int e = 0; e < 4; ++e) { float v = acc[ai][bj][m][n][e] * rs; if (isg) v = sigmoidf_(v + bv[bj][4 * n + e]); o[4 * n + e] = v; }
;                     u32x4 w; w.x = cvt_pk_bf16(o[0], o[1]); w.y = cvt_pk_bf16(o[2], o[3]); w.z = cvt_pk_bf16(o[4], o[5]); w.w = cvt_pk_bf16(o[6], o[7]);
;                     bf16_t* dst;
;                     if (tile < 4) dst = P + (size_t)row * PP + C_DQ + tile * BM + bj * HALF + cc;
;                     else if (tile < 8) dst = KD + ((size_t)((b * 8 + (tile - 4) * 2 + bj) * SEQ + t)) * 128 + cc;
;                     else if (tile < 12) dst = P + (size_t)row * PP + C_SQ + (tile - 8) * BM + bj * HALF + cc;
;                     else if (tile == 12) { const int ccf = bj * HALF + cc; dst = KS + ((size_t)((b * 4 + (ccf >> 6)) * SEQ + t)) * 64 + (ccf & 63); }
;                     else dst = P + (size_t)row * PP + C_GA + (tile - 13) * BM + bj * HALF + cc;
;                     *(u32x4*)dst = w;
	v_fmamk_f32 v113, v221, 0x3a800000, v170
	v_rsq_f32_e32 v113, v113
	s_mov_b64 s[94:95], -1
	s_and_b64 vcc, exec, s[14:15]
	v_mul_f32_e32 v113, v153, v113
	v_mul_f32_e32 v121, v108, v113
	v_fma_f32 v108, v108, v113, v187
	v_mul_f32_e32 v108, 0xbfb8aa3b, v108
	v_exp_f32_e32 v108, v108
	s_nop 0
	v_add_f32_e32 v108, 1.0, v108
	v_rcp_f32_e32 v108, v108
	s_nop 0
	v_cndmask_b32_e64 v108, v121, v108, s[10:11]
	v_mul_f32_e32 v121, v109, v113
	v_fma_f32 v109, v109, v113, v186
	v_mul_f32_e32 v109, 0xbfb8aa3b, v109
	v_exp_f32_e32 v109, v109
	s_nop 0
	v_add_f32_e32 v109, 1.0, v109
	v_rcp_f32_e32 v109, v109
	s_nop 0
	v_cndmask_b32_e64 v109, v121, v109, s[10:11]
	v_mul_f32_e32 v121, v110, v113
	v_fma_f32 v110, v110, v113, v191
	v_mul_f32_e32 v110, 0xbfb8aa3b, v110
	v_exp_f32_e32 v110, v110
	s_nop 0
	v_add_f32_e32 v110, 1.0, v110
	v_rcp_f32_e32 v110, v110
	s_nop 0
	v_cndmask_b32_e64 v110, v121, v110, s[10:11]
	v_mul_f32_e32 v121, v111, v113
	v_fma_f32 v111, v111, v113, v188
	v_mul_f32_e32 v111, 0xbfb8aa3b, v111
	v_exp_f32_e32 v111, v111
	s_nop 0
	v_add_f32_e32 v111, 1.0, v111
	v_rcp_f32_e32 v111, v111
	s_nop 0
	v_cndmask_b32_e64 v111, v121, v111, s[10:11]
	v_mul_f32_e32 v121, v104, v113
	v_fma_f32 v104, v104, v113, v192
	v_mul_f32_e32 v104, 0xbfb8aa3b, v104
	v_exp_f32_e32 v104, v104
	s_nop 0
	v_add_f32_e32 v104, 1.0, v104
	v_rcp_f32_e32 v104, v104
	s_nop 0
	v_cndmask_b32_e64 v121, v121, v104, s[10:11]
	v_mul_f32_e32 v104, v105, v113
	v_fma_f32 v105, v105, v113, v189
	v_mul_f32_e32 v105, 0xbfb8aa3b, v105
	v_exp_f32_e32 v105, v105
	s_nop 0
	v_add_f32_e32 v105, 1.0, v105
	v_rcp_f32_e32 v105, v105
	s_nop 0
	v_cndmask_b32_e64 v122, v104, v105, s[10:11]
	v_fma_f32 v105, v106, v113, v193
	v_mul_f32_e32 v105, 0xbfb8aa3b, v105
	v_exp_f32_e32 v105, v105
	v_mul_f32_e32 v104, v106, v113
	v_cvt_pk_bf16_f32 v106, v121, v122
	v_add_f32_e32 v105, 1.0, v105
	v_rcp_f32_e32 v105, v105
	s_nop 0
	v_cndmask_b32_e64 v123, v104, v105, s[10:11]
	v_fma_f32 v105, v107, v113, v190
	v_mul_f32_e32 v105, 0xbfb8aa3b, v105
	v_exp_f32_e32 v105, v105
	v_mul_f32_e32 v104, v107, v113
	v_add_f32_e32 v105, 1.0, v105
	v_rcp_f32_e32 v105, v105
	s_nop 0
	v_cndmask_b32_e64 v107, v104, v105, s[10:11]
	v_cvt_pk_bf16_f32 v104, v108, v109
	v_cvt_pk_bf16_f32 v105, v110, v111
	v_cvt_pk_bf16_f32 v107, v123, v107
	global_store_dwordx4 v[118:119], v[104:107], off nt
	s_cbranch_vccnz .LBB0_496
	s_and_b64 vcc, exec, s[12:13]
	s_mov_b64 s[6:7], -1
	s_cbranch_vccnz .LBB0_493
	s_andn2_b64 vcc, exec, s[90:91]
	s_cbranch_vccnz .LBB0_490
	s_andn2_b64 vcc, exec, s[88:89]
	s_cbranch_vccnz .LBB0_487
	v_lshl_add_u64 v[104:105], s[0:1], 1, v[116:117]
	v_lshl_add_u64 v[104:105], v[104:105], 0, v[136:137]
	v_lshl_add_u64 v[104:105], v[104:105], 0, s[36:37]
	s_mov_b64 s[6:7], 0

; __device__ __forceinline__ unsigned cvt_pk_bf16(float lo, float hi) { f32x2_t v = {lo, hi}; bf16x2_t b = __builtin_convertvector(v, bf16x2_t); return __builtin_bit_cast(unsigned, b); }
; __device__ __forceinline__ float sigmoidf_(float v) { return __builtin_amdgcn_rcpf(1.0f + __builtin_amdgcn_exp2f(-v * LOG2E)); }
;     __device__ __forceinline__ void operator()(const Acc& acc, const Unit& u, int wr, int wc, int fr, int fq) const {
;     ...
;                 const int b = row >> 11, t = row & (SEQ - 1);
; #pragma unroll
;                 for (int bj = 0; bj < 2; ++bj) {
;                     float o[8];
; #pragma unroll
;                     for (int n = 0; n < 2; ++n)
; #pragma unroll
;                         for (int e = 0; e < 4; ++e) { float v = acc[ai][bj][m][n][e] * rs; if (isg) v = sigmoidf_(v + bv[bj][4 * n + e]); o[4 * n + e] = v; }
;                     u32x4 w; w.x = cvt_pk_bf16(o[0], o[1]); w.y = cvt_pk_bf16(o[2], o[3]); w.z = cvt_pk_bf16(o[4], o[5]); w.w = cvt_pk_bf16(o[6], o[7]);
;                     bf16_t* dst;
;                     if (tile < 4) dst = P + (size_t)row * PP + C_DQ + tile * BM + bj * HALF + cc;
;                     else if (tile < 8) dst = KD + ((size_t)((b * 8 + (tile - 4) * 2 + bj) * SEQ + t)) * 128 + cc;
;                     else if (tile < 12) dst = P + (size_t)row * PP + C_SQ + (tile - 8) * BM + bj * HALF + cc;
;                     else if (tile == 12) { const int ccf = bj * HALF + cc; dst = KS + ((size_t)((b * 4 + (ccf >> 6)) * SEQ + t)) * 64 + (ccf & 63); }
;                     else dst = P + (size_t)row * PP + C_GA + (tile - 13) * BM + bj * HALF + cc;
;                     *(u32x4*)dst = w;
.LBB0_498:
	v_mul_f32_e32 v106, v100, v113
	v_fma_f32 v100, v100, v113, v181
	v_mul_f32_e32 v100, 0xbfb8aa3b, v100
	v_exp_f32_e32 v100, v100
	s_movk_i32 s6, 0x7ef
	s_mov_b64 s[94:95], -1
	s_and_b64 vcc, exec, s[14:15]
	v_add_f32_e32 v100, 1.0, v100
	v_rcp_f32_e32 v100, v100
	s_nop 0
	v_cndmask_b32_e64 v100, v106, v100, s[10:11]
	v_mul_f32_e32 v106, v101, v113
	v_fma_f32 v101, v101, v113, v174
	v_mul_f32_e32 v101, 0xbfb8aa3b, v101
	v_exp_f32_e32 v101, v101
	s_nop 0
	v_add_f32_e32 v101, 1.0, v101
	v_rcp_f32_e32 v101, v101
	s_nop 0
	v_cndmask_b32_e64 v101, v106, v101, s[10:11]
	v_mul_f32_e32 v106, v102, v113
	v_fma_f32 v102, v102, v113, v183
	v_mul_f32_e32 v102, 0xbfb8aa3b, v102
	v_exp_f32_e32 v102, v102
	s_nop 0
	v_add_f32_e32 v102, 1.0, v102
	v_rcp_f32_e32 v102, v102
	s_nop 0
	v_cndmask_b32_e64 v102, v106, v102, s[10:11]
	v_mul_f32_e32 v106, v103, v113
	v_fma_f32 v103, v103, v113, v178
	v_mul_f32_e32 v103, 0xbfb8aa3b, v103
	v_exp_f32_e32 v103, v103
	s_nop 0
	v_add_f32_e32 v103, 1.0, v103
	v_rcp_f32_e32 v103, v103
	s_nop 0
	v_cndmask_b32_e64 v103, v106, v103, s[10:11]
	v_mul_f32_e32 v106, v96, v113
	v_fma_f32 v96, v96, v113, v184
	v_mul_f32_e32 v96, 0xbfb8aa3b, v96
	v_exp_f32_e32 v96, v96
	s_nop 0
	v_add_f32_e32 v96, 1.0, v96
	v_rcp_f32_e32 v96, v96
	s_nop 0
	v_cndmask_b32_e64 v106, v106, v96, s[10:11]
	v_mul_f32_e32 v96, v97, v113
	v_fma_f32 v97, v97, v113, v180
	v_mul_f32_e32 v97, 0xbfb8aa3b, v97
	v_exp_f32_e32 v97, v97
	s_nop 0
	v_add_f32_e32 v97, 1.0, v97
	v_rcp_f32_e32 v97, v97
	s_nop 0
	v_cndmask_b32_e64 v107, v96, v97, s[10:11]
	v_fma_f32 v97, v98, v113, v185
	v_mul_f32_e32 v97, 0xbfb8aa3b, v97
	v_exp_f32_e32 v97, v97
	v_mul_f32_e32 v96, v98, v113
	v_cvt_pk_bf16_f32 v98, v106, v107
	v_add_f32_e32 v97, 1.0, v97
	v_rcp_f32_e32 v97, v97
	s_nop 0
	v_cndmask_b32_e64 v108, v96, v97, s[10:11]
	v_fma_f32 v97, v99, v113, v182
	v_mul_f32_e32 v97, 0xbfb8aa3b, v97
	v_exp_f32_e32 v97, v97
	v_mul_f32_e32 v96, v99, v113
	v_add_f32_e32 v97, 1.0, v97
	v_rcp_f32_e32 v97, v97
	s_nop 0
	v_cndmask_b32_e64 v99, v96, v97, s[10:11]
	v_cvt_pk_bf16_f32 v96, v100, v101
	v_cvt_pk_bf16_f32 v97, v102, v103
	v_cvt_pk_bf16_f32 v99, v108, v99
	global_store_dwordx4 v[104:105], v[96:99], off nt
	v_bitop3_b32 v104, v152, s6, 32 bitop3:0xc8
	s_nop 0
	v_or_b32_e32 v96, 32, v152
	v_ashrrev_i32_e32 v97, 31, v96
	v_lshl_add_u64 v[98:99], v[96:97], 2, s[44:45]
	s_nop 0
	v_lshlrev_b64 v[98:99], 13, v[96:97]
	v_or_b32_e32 v96, s17, v104
	s_cbranch_vccnz .LBB0_512
	s_and_b64 vcc, exec, s[12:13]
	s_mov_b64 s[6:7], -1
	s_cbranch_vccnz .LBB0_509
	s_andn2_b64 vcc, exec, s[90:91]
	s_cbranch_vccnz .LBB0_506
	s_andn2_b64 vcc, exec, s[88:89]
	s_cbranch_vccnz .LBB0_503
	v_lshl_add_u64 v[100:101], s[20:21], 0, v[98:99]
	v_lshl_add_u64 v[100:101], s[0:1], 1, v[100:101]
	v_lshl_add_u64 v[100:101], v[100:101], 0, v[136:137]
	v_lshl_add_u64 v[102:103], v[100:101], 0, s[30:31]
	s_mov_b64 s[6:7], 0

;     __device__ __forceinline__ void operator()(const Acc& acc, const Unit& u, int wr, int wc, int fr, int fq) const {
;     ...
;                     bf16_t* dst;
;                     if (tile < 4) dst = P + (size_t)row * PP + C_DQ + tile * BM + bj * HALF + cc;
;                     else if (tile < 8) dst = KD + ((size_t)((b * 8 + (tile - 4) * 2 + bj) * SEQ + t)) * 128 + cc;
;                     else if (tile < 12) dst = P + (size_t)row * PP + C_SQ + (tile - 8) * BM + bj * HALF + cc;
;                     else if (tile == 12) { const int ccf = bj * HALF + cc; dst = KS + ((size_t)((b * 4 + (ccf >> 6)) * SEQ + t)) * 64 + (ccf & 63); }
;                     else dst = P + (size_t)row * PP + C_GA + (tile - 13) * BM + bj * HALF + cc;
;                     *(u32x4*)dst = w;
.LBB0_514:

; __device__ __forceinline__ unsigned cvt_pk_bf16(float lo, float hi) { f32x2_t v = {lo, hi}; bf16x2_t b = __builtin_convertvector(v, bf16x2_t); return __builtin_bit_cast(unsigned, b); }
; __device__ __forceinline__ float rstd_of(const float* ss, int row) { return __builtin_amdgcn_rsqf(ss[row] * (1.0f / 1024.0f) + RMS_EPS); }
; __device__ __forceinline__ float sigmoidf_(float v) { return __builtin_amdgcn_rcpf(1.0f + __builtin_amdgcn_exp2f(-v * LOG2E)); }
;     __device__ __forceinline__ void operator()(const Acc& acc, const Unit& u, int wr, int wc, int fr, int fq) const {
;     ...
;                 const int row = row0 + ai * HALF + m * 16; const float rs = rstd_of(ss, row) * sc;
;                 const int b = row >> 11, t = row & (SEQ - 1);
; #pragma unroll
;                 for (int bj = 0; bj < 2; ++bj) {
;                     float o[8];
; #pragma unroll
;                     for (int n = 0; n < 2; ++n)
; #pragma unroll
;                         for (int e = 0; e < 4; ++e) { float v = acc[ai][bj][m][n][e] * rs; if (isg) v = sigmoidf_(v + bv[bj][4 * n + e]); o[4 * n + e] = v; }
;                     u32x4 w; w.x = cvt_pk_bf16(o[0], o[1]); w.y = cvt_pk_bf16(o[2], o[3]); w.z = cvt_pk_bf16(o[4], o[5]); w.w = cvt_pk_bf16(o[6], o[7]);
;                     bf16_t* dst;
;                     if (tile < 4) dst = P + (size_t)row * PP + C_DQ + tile * BM + bj * HALF + cc;
;                     else if (tile < 8) dst = KD + ((size_t)((b * 8 + (tile - 4) * 2 + bj) * SEQ + t)) * 128 + cc;
;                     else if (tile < 12) dst = P + (size_t)row * PP + C_SQ + (tile - 8) * BM + bj * HALF + cc;
;                     else if (tile == 12) { const int ccf = bj * HALF + cc; dst = KS + ((size_t)((b * 4 + (ccf >> 6)) * SEQ + t)) * 64 + (ccf & 63); }
;                     else dst = P + (size_t)row * PP + C_GA + (tile - 13) * BM + bj * HALF + cc;
;                     *(u32x4*)dst = w;
	v_fmamk_f32 v97, v222, 0x3a800000, v170
	v_rsq_f32_e32 v97, v97
	s_mov_b64 s[94:95], -1
	s_and_b64 vcc, exec, s[14:15]
	v_mul_f32_e32 v97, v153, v97
	v_mul_f32_e32 v105, v92, v97
	v_fma_f32 v92, v92, v97, v187
	v_mul_f32_e32 v92, 0xbfb8aa3b, v92
	v_exp_f32_e32 v92, v92
	s_nop 0
	v_add_f32_e32 v92, 1.0, v92
	v_rcp_f32_e32 v92, v92
	s_nop 0
	v_cndmask_b32_e64 v92, v105, v92, s[10:11]
	v_mul_f32_e32 v105, v93, v97
	v_fma_f32 v93, v93, v97, v186
	v_mul_f32_e32 v93, 0xbfb8aa3b, v93
	v_exp_f32_e32 v93, v93
	s_nop 0
	v_add_f32_e32 v93, 1.0, v93
	v_rcp_f32_e32 v93, v93
	s_nop 0
	v_cndmask_b32_e64 v93, v105, v93, s[10:11]
	v_mul_f32_e32 v105, v94, v97
	v_fma_f32 v94, v94, v97, v191
	v_mul_f32_e32 v94, 0xbfb8aa3b, v94
	v_exp_f32_e32 v94, v94
	s_nop 0
	v_add_f32_e32 v94, 1.0, v94
	v_rcp_f32_e32 v94, v94
	s_nop 0
	v_cndmask_b32_e64 v94, v105, v94, s[10:11]
	v_mul_f32_e32 v105, v95, v97
	v_fma_f32 v95, v95, v97, v188
	v_mul_f32_e32 v95, 0xbfb8aa3b, v95
	v_exp_f32_e32 v95, v95
	s_nop 0
	v_add_f32_e32 v95, 1.0, v95
	v_rcp_f32_e32 v95, v95
	s_nop 0
	v_cndmask_b32_e64 v95, v105, v95, s[10:11]
	v_mul_f32_e32 v105, v88, v97
	v_fma_f32 v88, v88, v97, v192
	v_mul_f32_e32 v88, 0xbfb8aa3b, v88
	v_exp_f32_e32 v88, v88
	s_nop 0
	v_add_f32_e32 v88, 1.0, v88
	v_rcp_f32_e32 v88, v88
	s_nop 0
	v_cndmask_b32_e64 v105, v105, v88, s[10:11]
	v_mul_f32_e32 v88, v89, v97
	v_fma_f32 v89, v89, v97, v189
	v_mul_f32_e32 v89, 0xbfb8aa3b, v89
	v_exp_f32_e32 v89, v89
	s_nop 0
	v_add_f32_e32 v89, 1.0, v89
	v_rcp_f32_e32 v89, v89
	s_nop 0
	v_cndmask_b32_e64 v106, v88, v89, s[10:11]
	v_fma_f32 v89, v90, v97, v193
	v_mul_f32_e32 v89, 0xbfb8aa3b, v89
	v_exp_f32_e32 v89, v89
	v_mul_f32_e32 v88, v90, v97
	v_cvt_pk_bf16_f32 v90, v105, v106
	v_add_f32_e32 v89, 1.0, v89
	v_rcp_f32_e32 v89, v89
	s_nop 0
	v_cndmask_b32_e64 v107, v88, v89, s[10:11]
	v_fma_f32 v89, v91, v97, v190
	v_mul_f32_e32 v89, 0xbfb8aa3b, v89
	v_exp_f32_e32 v89, v89
	v_mul_f32_e32 v88, v91, v97
	v_add_f32_e32 v89, 1.0, v89
	v_rcp_f32_e32 v89, v89
	s_nop 0
	v_cndmask_b32_e64 v91, v88, v89, s[10:11]
	v_cvt_pk_bf16_f32 v88, v92, v93
	v_cvt_pk_bf16_f32 v89, v94, v95
	v_cvt_pk_bf16_f32 v91, v107, v91
	global_store_dwordx4 v[102:103], v[88:91], off nt
	s_cbranch_vccnz .LBB0_528
	s_and_b64 vcc, exec, s[12:13]
	s_mov_b64 s[6:7], -1
	s_cbranch_vccnz .LBB0_525
	s_andn2_b64 vcc, exec, s[90:91]
	s_cbranch_vccnz .LBB0_522
	s_andn2_b64 vcc, exec, s[88:89]
	s_cbranch_vccnz .LBB0_519
	v_lshl_add_u64 v[88:89], s[0:1], 1, v[100:101]
	v_lshl_add_u64 v[88:89], v[88:89], 0, v[136:137]
	v_lshl_add_u64 v[88:89], v[88:89], 0, s[36:37]
	s_mov_b64 s[6:7], 0

; __device__ __forceinline__ unsigned cvt_pk_bf16(float lo, float hi) { f32x2_t v = {lo, hi}; bf16x2_t b = __builtin_convertvector(v, bf16x2_t); return __builtin_bit_cast(unsigned, b); }
; __device__ __forceinline__ float sigmoidf_(float v) { return __builtin_amdgcn_rcpf(1.0f + __builtin_amdgcn_exp2f(-v * LOG2E)); }
;     __device__ __forceinline__ void operator()(const Acc& acc, const Unit& u, int wr, int wc, int fr, int fq) const {
;     ...
;                 const int b = row >> 11, t = row & (SEQ - 1);
; #pragma unroll
;                 for (int bj = 0; bj < 2; ++bj) {
;                     float o[8];
; #pragma unroll
;                     for (int n = 0; n < 2; ++n)
; #pragma unroll
;                         for (int e = 0; e < 4; ++e) { float v = acc[ai][bj][m][n][e] * rs; if (isg) v = sigmoidf_(v + bv[bj][4 * n + e]); o[4 * n + e] = v; }
;                     u32x4 w; w.x = cvt_pk_bf16(o[0], o[1]); w.y = cvt_pk_bf16(o[2], o[3]); w.z = cvt_pk_bf16(o[4], o[5]); w.w = cvt_pk_bf16(o[6], o[7]);
;                     bf16_t* dst;
;                     if (tile < 4) dst = P + (size_t)row * PP + C_DQ + tile * BM + bj * HALF + cc;
;                     else if (tile < 8) dst = KD + ((size_t)((b * 8 + (tile - 4) * 2 + bj) * SEQ + t)) * 128 + cc;
;                     else if (tile < 12) dst = P + (size_t)row * PP + C_SQ + (tile - 8) * BM + bj * HALF + cc;
;                     else if (tile == 12) { const int ccf = bj * HALF + cc; dst = KS + ((size_t)((b * 4 + (ccf >> 6)) * SEQ + t)) * 64 + (ccf & 63); }
;                     else dst = P + (size_t)row * PP + C_GA + (tile - 13) * BM + bj * HALF + cc;
;                     *(u32x4*)dst = w;
.LBB0_530:
	v_mul_f32_e32 v90, v84, v97
	v_fma_f32 v84, v84, v97, v181
	v_mul_f32_e32 v84, 0xbfb8aa3b, v84
	v_exp_f32_e32 v84, v84
	s_movk_i32 s6, 0x7ff
	s_mov_b64 s[94:95], -1
	s_and_b64 vcc, exec, s[14:15]
	v_add_f32_e32 v84, 1.0, v84
	v_rcp_f32_e32 v84, v84
	s_nop 0
	v_cndmask_b32_e64 v84, v90, v84, s[10:11]
	v_mul_f32_e32 v90, v85, v97
	v_fma_f32 v85, v85, v97, v174
	v_mul_f32_e32 v85, 0xbfb8aa3b, v85
	v_exp_f32_e32 v85, v85
	s_nop 0
	v_add_f32_e32 v85, 1.0, v85
	v_rcp_f32_e32 v85, v85
	s_nop 0
	v_cndmask_b32_e64 v85, v90, v85, s[10:11]
	v_mul_f32_e32 v90, v86, v97
	v_fma_f32 v86, v86, v97, v183
	v_mul_f32_e32 v86, 0xbfb8aa3b, v86
	v_exp_f32_e32 v86, v86
	s_nop 0
	v_add_f32_e32 v86, 1.0, v86
	v_rcp_f32_e32 v86, v86
	s_nop 0
	v_cndmask_b32_e64 v86, v90, v86, s[10:11]
	v_mul_f32_e32 v90, v87, v97
	v_fma_f32 v87, v87, v97, v178
	v_mul_f32_e32 v87, 0xbfb8aa3b, v87
	v_exp_f32_e32 v87, v87
	s_nop 0
	v_add_f32_e32 v87, 1.0, v87
	v_rcp_f32_e32 v87, v87
	s_nop 0
	v_cndmask_b32_e64 v87, v90, v87, s[10:11]
	v_mul_f32_e32 v90, v80, v97
	v_fma_f32 v80, v80, v97, v184
	v_mul_f32_e32 v80, 0xbfb8aa3b, v80
	v_exp_f32_e32 v80, v80
	s_nop 0
	v_add_f32_e32 v80, 1.0, v80
	v_rcp_f32_e32 v80, v80
	s_nop 0
	v_cndmask_b32_e64 v90, v90, v80, s[10:11]
	v_mul_f32_e32 v80, v81, v97
	v_fma_f32 v81, v81, v97, v180
	v_mul_f32_e32 v81, 0xbfb8aa3b, v81
	v_exp_f32_e32 v81, v81
	s_nop 0
	v_add_f32_e32 v81, 1.0, v81
	v_rcp_f32_e32 v81, v81
	s_nop 0
	v_cndmask_b32_e64 v91, v80, v81, s[10:11]
	v_fma_f32 v81, v82, v97, v185
	v_mul_f32_e32 v81, 0xbfb8aa3b, v81
	v_exp_f32_e32 v81, v81
	v_mul_f32_e32 v80, v82, v97
	v_cvt_pk_bf16_f32 v82, v90, v91
	v_add_f32_e32 v81, 1.0, v81
	v_rcp_f32_e32 v81, v81
	s_nop 0
	v_cndmask_b32_e64 v92, v80, v81, s[10:11]
	v_fma_f32 v81, v83, v97, v182
	v_mul_f32_e32 v81, 0xbfb8aa3b, v81
	v_exp_f32_e32 v81, v81
	v_mul_f32_e32 v80, v83, v97
	v_add_f32_e32 v81, 1.0, v81
	v_rcp_f32_e32 v81, v81
	s_nop 0
	v_cndmask_b32_e64 v83, v80, v81, s[10:11]
	v_cvt_pk_bf16_f32 v80, v84, v85
	v_cvt_pk_bf16_f32 v81, v86, v87
	v_cvt_pk_bf16_f32 v83, v92, v83
	global_store_dwordx4 v[88:89], v[80:83], off nt
	v_bitop3_b32 v88, v152, s6, 48 bitop3:0xc8
	s_nop 0
	v_or_b32_e32 v80, 48, v152
	v_ashrrev_i32_e32 v81, 31, v80
	v_lshl_add_u64 v[82:83], v[80:81], 2, s[44:45]
	s_nop 0
	v_lshlrev_b64 v[82:83], 13, v[80:81]
	v_or_b32_e32 v80, s17, v88
	s_cbranch_vccnz .LBB0_544
	s_and_b64 vcc, exec, s[12:13]
	s_mov_b64 s[6:7], -1
	s_cbranch_vccnz .LBB0_541
	s_andn2_b64 vcc, exec, s[90:91]
	s_cbranch_vccnz .LBB0_538
	s_andn2_b64 vcc, exec, s[88:89]
	s_cbranch_vccnz .LBB0_535
	v_lshl_add_u64 v[84:85], s[20:21], 0, v[82:83]
	v_lshl_add_u64 v[84:85], s[0:1], 1, v[84:85]
	v_lshl_add_u64 v[84:85], v[84:85], 0, v[136:137]
	v_lshl_add_u64 v[86:87], v[84:85], 0, s[30:31]
	s_mov_b64 s[6:7], 0

;     __device__ __forceinline__ void operator()(const Acc& acc, const Unit& u, int wr, int wc, int fr, int fq) const {
;     ...
;                     bf16_t* dst;
;                     if (tile < 4) dst = P + (size_t)row * PP + C_DQ + tile * BM + bj * HALF + cc;
;                     else if (tile < 8) dst = KD + ((size_t)((b * 8 + (tile - 4) * 2 + bj) * SEQ + t)) * 128 + cc;
;                     else if (tile < 12) dst = P + (size_t)row * PP + C_SQ + (tile - 8) * BM + bj * HALF + cc;
;                     else if (tile == 12) { const int ccf = bj * HALF + cc; dst = KS + ((size_t)((b * 4 + (ccf >> 6)) * SEQ + t)) * 64 + (ccf & 63); }
;                     else dst = P + (size_t)row * PP + C_GA + (tile - 13) * BM + bj * HALF + cc;
;                     *(u32x4*)dst = w;
.LBB0_546:

; __device__ __forceinline__ unsigned cvt_pk_bf16(float lo, float hi) { f32x2_t v = {lo, hi}; bf16x2_t b = __builtin_convertvector(v, bf16x2_t); return __builtin_bit_cast(unsigned, b); }
; __device__ __forceinline__ float rstd_of(const float* ss, int row) { return __builtin_amdgcn_rsqf(ss[row] * (1.0f / 1024.0f) + RMS_EPS); }
; __device__ __forceinline__ float sigmoidf_(float v) { return __builtin_amdgcn_rcpf(1.0f + __builtin_amdgcn_exp2f(-v * LOG2E)); }
;     __device__ __forceinline__ void operator()(const Acc& acc, const Unit& u, int wr, int wc, int fr, int fq) const {
;     ...
;                 const int row = row0 + ai * HALF + m * 16; const float rs = rstd_of(ss, row) * sc;
;                 const int b = row >> 11, t = row & (SEQ - 1);
; #pragma unroll
;                 for (int bj = 0; bj < 2; ++bj) {
;                     float o[8];
; #pragma unroll
;                     for (int n = 0; n < 2; ++n)
; #pragma unroll
;                         for (int e = 0; e < 4; ++e) { float v = acc[ai][bj][m][n][e] * rs; if (isg) v = sigmoidf_(v + bv[bj][4 * n + e]); o[4 * n + e] = v; }
;                     u32x4 w; w.x = cvt_pk_bf16(o[0], o[1]); w.y = cvt_pk_bf16(o[2], o[3]); w.z = cvt_pk_bf16(o[4], o[5]); w.w = cvt_pk_bf16(o[6], o[7]);
;                     bf16_t* dst;
;                     if (tile < 4) dst = P + (size_t)row * PP + C_DQ + tile * BM + bj * HALF + cc;
;                     else if (tile < 8) dst = KD + ((size_t)((b * 8 + (tile - 4) * 2 + bj) * SEQ + t)) * 128 + cc;
;                     else if (tile < 12) dst = P + (size_t)row * PP + C_SQ + (tile - 8) * BM + bj * HALF + cc;
;                     else if (tile == 12) { const int ccf = bj * HALF + cc; dst = KS + ((size_t)((b * 4 + (ccf >> 6)) * SEQ + t)) * 64 + (ccf & 63); }
;                     else dst = P + (size_t)row * PP + C_GA + (tile - 13) * BM + bj * HALF + cc;
;                     *(u32x4*)dst = w;
	v_fmamk_f32 v81, v223, 0x3a800000, v170
	v_rsq_f32_e32 v81, v81
	s_mov_b64 s[94:95], -1
	s_and_b64 vcc, exec, s[14:15]
	v_mul_f32_e32 v81, v153, v81
	v_mul_f32_e32 v89, v76, v81
	v_fma_f32 v76, v76, v81, v187
	v_mul_f32_e32 v76, 0xbfb8aa3b, v76
	v_exp_f32_e32 v76, v76
	s_nop 0
	v_add_f32_e32 v76, 1.0, v76
	v_rcp_f32_e32 v76, v76
	s_nop 0
	v_cndmask_b32_e64 v76, v89, v76, s[10:11]
	v_mul_f32_e32 v89, v77, v81
	v_fma_f32 v77, v77, v81, v186
	v_mul_f32_e32 v77, 0xbfb8aa3b, v77
	v_exp_f32_e32 v77, v77
	s_nop 0
	v_add_f32_e32 v77, 1.0, v77
	v_rcp_f32_e32 v77, v77
	s_nop 0
	v_cndmask_b32_e64 v77, v89, v77, s[10:11]
	v_mul_f32_e32 v89, v78, v81
	v_fma_f32 v78, v78, v81, v191
	v_mul_f32_e32 v78, 0xbfb8aa3b, v78
	v_exp_f32_e32 v78, v78
	s_nop 0
	v_add_f32_e32 v78, 1.0, v78
	v_rcp_f32_e32 v78, v78
	s_nop 0
	v_cndmask_b32_e64 v78, v89, v78, s[10:11]
	v_mul_f32_e32 v89, v79, v81
	v_fma_f32 v79, v79, v81, v188
	v_mul_f32_e32 v79, 0xbfb8aa3b, v79
	v_exp_f32_e32 v79, v79
	s_nop 0
	v_add_f32_e32 v79, 1.0, v79
	v_rcp_f32_e32 v79, v79
	s_nop 0
	v_cndmask_b32_e64 v79, v89, v79, s[10:11]
	v_mul_f32_e32 v89, v72, v81
	v_fma_f32 v72, v72, v81, v192
	v_mul_f32_e32 v72, 0xbfb8aa3b, v72
	v_exp_f32_e32 v72, v72
	s_nop 0
	v_add_f32_e32 v72, 1.0, v72
	v_rcp_f32_e32 v72, v72
	s_nop 0
	v_cndmask_b32_e64 v89, v89, v72, s[10:11]
	v_mul_f32_e32 v72, v73, v81
	v_fma_f32 v73, v73, v81, v189
	v_mul_f32_e32 v73, 0xbfb8aa3b, v73
	v_exp_f32_e32 v73, v73
	s_nop 0
	v_add_f32_e32 v73, 1.0, v73
	v_rcp_f32_e32 v73, v73
	s_nop 0
	v_cndmask_b32_e64 v90, v72, v73, s[10:11]
	v_fma_f32 v73, v74, v81, v193
	v_mul_f32_e32 v73, 0xbfb8aa3b, v73
	v_exp_f32_e32 v73, v73
	v_mul_f32_e32 v72, v74, v81
	v_cvt_pk_bf16_f32 v74, v89, v90
	v_add_f32_e32 v73, 1.0, v73
	v_rcp_f32_e32 v73, v73
	s_nop 0
	v_cndmask_b32_e64 v91, v72, v73, s[10:11]
	v_fma_f32 v73, v75, v81, v190
	v_mul_f32_e32 v73, 0xbfb8aa3b, v73
	v_exp_f32_e32 v73, v73
	v_mul_f32_e32 v72, v75, v81
	v_add_f32_e32 v73, 1.0, v73
	v_rcp_f32_e32 v73, v73
	s_nop 0
	v_cndmask_b32_e64 v75, v72, v73, s[10:11]
	v_cvt_pk_bf16_f32 v72, v76, v77
	v_cvt_pk_bf16_f32 v73, v78, v79
	v_cvt_pk_bf16_f32 v75, v91, v75
	global_store_dwordx4 v[86:87], v[72:75], off nt
	s_cbranch_vccnz .LBB0_560
	s_and_b64 vcc, exec, s[12:13]
	s_mov_b64 s[6:7], -1
	s_cbranch_vccnz .LBB0_557
	s_andn2_b64 vcc, exec, s[90:91]
	s_cbranch_vccnz .LBB0_554
	s_andn2_b64 vcc, exec, s[88:89]
	s_cbranch_vccnz .LBB0_551
	v_lshl_add_u64 v[72:73], s[0:1], 1, v[84:85]
	v_lshl_add_u64 v[72:73], v[72:73], 0, v[136:137]
	v_lshl_add_u64 v[72:73], v[72:73], 0, s[36:37]
	s_mov_b64 s[6:7], 0

; __device__ __forceinline__ unsigned cvt_pk_bf16(float lo, float hi) { f32x2_t v = {lo, hi}; bf16x2_t b = __builtin_convertvector(v, bf16x2_t); return __builtin_bit_cast(unsigned, b); }
; __device__ __forceinline__ float sigmoidf_(float v) { return __builtin_amdgcn_rcpf(1.0f + __builtin_amdgcn_exp2f(-v * LOG2E)); }
;     __device__ __forceinline__ void operator()(const Acc& acc, const Unit& u, int wr, int wc, int fr, int fq) const {
;     ...
;                 const int b = row >> 11, t = row & (SEQ - 1);
; #pragma unroll
;                 for (int bj = 0; bj < 2; ++bj) {
;                     float o[8];
; #pragma unroll
;                     for (int n = 0; n < 2; ++n)
; #pragma unroll
;                         for (int e = 0; e < 4; ++e) { float v = acc[ai][bj][m][n][e] * rs; if (isg) v = sigmoidf_(v + bv[bj][4 * n + e]); o[4 * n + e] = v; }
;                     u32x4 w; w.x = cvt_pk_bf16(o[0], o[1]); w.y = cvt_pk_bf16(o[2], o[3]); w.z = cvt_pk_bf16(o[4], o[5]); w.w = cvt_pk_bf16(o[6], o[7]);
;                     bf16_t* dst;
;                     if (tile < 4) dst = P + (size_t)row * PP + C_DQ + tile * BM + bj * HALF + cc;
;                     else if (tile < 8) dst = KD + ((size_t)((b * 8 + (tile - 4) * 2 + bj) * SEQ + t)) * 128 + cc;
;                     else if (tile < 12) dst = P + (size_t)row * PP + C_SQ + (tile - 8) * BM + bj * HALF + cc;
;                     else if (tile == 12) { const int ccf = bj * HALF + cc; dst = KS + ((size_t)((b * 4 + (ccf >> 6)) * SEQ + t)) * 64 + (ccf & 63); }
;                     else dst = P + (size_t)row * PP + C_GA + (tile - 13) * BM + bj * HALF + cc;
;                     *(u32x4*)dst = w;
.LBB0_562:
	v_mul_f32_e32 v74, v68, v81
	v_fma_f32 v68, v68, v81, v181
	v_mul_f32_e32 v68, 0xbfb8aa3b, v68
	v_exp_f32_e32 v68, v68
	s_mov_b64 s[94:95], -1
	s_and_b64 vcc, exec, s[14:15]
	v_add_f32_e32 v68, 1.0, v68
	v_rcp_f32_e32 v68, v68
	s_nop 0
	v_cndmask_b32_e64 v68, v74, v68, s[10:11]
	v_mul_f32_e32 v74, v69, v81
	v_fma_f32 v69, v69, v81, v174
	v_mul_f32_e32 v69, 0xbfb8aa3b, v69
	v_exp_f32_e32 v69, v69
	s_nop 0
	v_add_f32_e32 v69, 1.0, v69
	v_rcp_f32_e32 v69, v69
	s_nop 0
	v_cndmask_b32_e64 v69, v74, v69, s[10:11]
	v_mul_f32_e32 v74, v70, v81
	v_fma_f32 v70, v70, v81, v183
	v_mul_f32_e32 v70, 0xbfb8aa3b, v70
	v_exp_f32_e32 v70, v70
	s_nop 0
	v_add_f32_e32 v70, 1.0, v70
	v_rcp_f32_e32 v70, v70
	s_nop 0
	v_cndmask_b32_e64 v70, v74, v70, s[10:11]
	v_mul_f32_e32 v74, v71, v81
	v_fma_f32 v71, v71, v81, v178
	v_mul_f32_e32 v71, 0xbfb8aa3b, v71
	v_exp_f32_e32 v71, v71
	s_nop 0
	v_add_f32_e32 v71, 1.0, v71
	v_rcp_f32_e32 v71, v71
	s_nop 0
	v_cndmask_b32_e64 v71, v74, v71, s[10:11]
	v_mul_f32_e32 v74, v64, v81
	v_fma_f32 v64, v64, v81, v184
	v_mul_f32_e32 v64, 0xbfb8aa3b, v64
	v_exp_f32_e32 v64, v64
	s_nop 0
	v_add_f32_e32 v64, 1.0, v64
	v_rcp_f32_e32 v64, v64
	s_nop 0
	v_cndmask_b32_e64 v74, v74, v64, s[10:11]
	v_mul_f32_e32 v64, v65, v81
	v_fma_f32 v65, v65, v81, v180
	v_mul_f32_e32 v65, 0xbfb8aa3b, v65
	v_exp_f32_e32 v65, v65
	s_nop 0
	v_add_f32_e32 v65, 1.0, v65
	v_rcp_f32_e32 v65, v65
	s_nop 0
	v_cndmask_b32_e64 v75, v64, v65, s[10:11]
	v_fma_f32 v65, v66, v81, v185
	v_mul_f32_e32 v65, 0xbfb8aa3b, v65
	v_exp_f32_e32 v65, v65
	v_mul_f32_e32 v64, v66, v81
	v_cvt_pk_bf16_f32 v66, v74, v75
	v_add_f32_e32 v65, 1.0, v65
	v_rcp_f32_e32 v65, v65
	s_nop 0
	v_cndmask_b32_e64 v76, v64, v65, s[10:11]
	v_fma_f32 v65, v67, v81, v182
	v_mul_f32_e32 v65, 0xbfb8aa3b, v65
	v_exp_f32_e32 v65, v65
	v_mul_f32_e32 v64, v67, v81
	v_add_f32_e32 v65, 1.0, v65
	v_rcp_f32_e32 v65, v65
	s_nop 0
	v_cndmask_b32_e64 v67, v64, v65, s[10:11]
	v_cvt_pk_bf16_f32 v64, v68, v69
	v_cvt_pk_bf16_f32 v65, v70, v71
	v_cvt_pk_bf16_f32 v67, v76, v67
	global_store_dwordx4 v[72:73], v[64:67], off nt
	s_nop 0
	s_nop 0
	v_add_u32_e32 v64, 0x80, v152
	v_ashrrev_i32_e32 v65, 11, v64
	v_lshl_or_b32 v73, v65, 13, s23
	v_lshl_add_u32 v72, v65, 3, s2
	v_ashrrev_i32_e32 v65, 31, v64
	v_and_b32_e32 v74, 0x7cf, v64
	v_lshlrev_b64 v[66:67], 13, v[64:65]
	v_or_b32_e32 v64, v73, v74
	s_cbranch_vccnz .LBB0_576
	s_and_b64 vcc, exec, s[12:13]
	s_mov_b64 s[6:7], -1
	s_cbranch_vccnz .LBB0_573
	s_andn2_b64 vcc, exec, s[90:91]
	s_cbranch_vccnz .LBB0_570
	s_andn2_b64 vcc, exec, s[88:89]
	s_cbranch_vccnz .LBB0_567
	v_lshl_add_u64 v[68:69], s[20:21], 0, v[66:67]
	v_lshl_add_u64 v[68:69], s[0:1], 1, v[68:69]
	v_lshl_add_u64 v[68:69], v[68:69], 0, v[136:137]
	v_lshl_add_u64 v[70:71], v[68:69], 0, s[30:31]
	s_mov_b64 s[6:7], 0

;     __device__ __forceinline__ void operator()(const Acc& acc, const Unit& u, int wr, int wc, int fr, int fq) const {
;     ...
;                     bf16_t* dst;
;                     if (tile < 4) dst = P + (size_t)row * PP + C_DQ + tile * BM + bj * HALF + cc;
;                     else if (tile < 8) dst = KD + ((size_t)((b * 8 + (tile - 4) * 2 + bj) * SEQ + t)) * 128 + cc;
;                     else if (tile < 12) dst = P + (size_t)row * PP + C_SQ + (tile - 8) * BM + bj * HALF + cc;
;                     else if (tile == 12) { const int ccf = bj * HALF + cc; dst = KS + ((size_t)((b * 4 + (ccf >> 6)) * SEQ + t)) * 64 + (ccf & 63); }
;                     else dst = P + (size_t)row * PP + C_GA + (tile - 13) * BM + bj * HALF + cc;
;                     *(u32x4*)dst = w;
.LBB0_578:

; __device__ __forceinline__ unsigned cvt_pk_bf16(float lo, float hi) { f32x2_t v = {lo, hi}; bf16x2_t b = __builtin_convertvector(v, bf16x2_t); return __builtin_bit_cast(unsigned, b); }
; __device__ __forceinline__ float rstd_of(const float* ss, int row) { return __builtin_amdgcn_rsqf(ss[row] * (1.0f / 1024.0f) + RMS_EPS); }
; __device__ __forceinline__ float sigmoidf_(float v) { return __builtin_amdgcn_rcpf(1.0f + __builtin_amdgcn_exp2f(-v * LOG2E)); }
;     __device__ __forceinline__ void operator()(const Acc& acc, const Unit& u, int wr, int wc, int fr, int fq) const {
;     ...
;                 const int row = row0 + ai * HALF + m * 16; const float rs = rstd_of(ss, row) * sc;
;                 const int b = row >> 11, t = row & (SEQ - 1);
; #pragma unroll
;                 for (int bj = 0; bj < 2; ++bj) {
;                     float o[8];
; #pragma unroll
;                     for (int n = 0; n < 2; ++n)
; #pragma unroll
;                         for (int e = 0; e < 4; ++e) { float v = acc[ai][bj][m][n][e] * rs; if (isg) v = sigmoidf_(v + bv[bj][4 * n + e]); o[4 * n + e] = v; }
;                     u32x4 w; w.x = cvt_pk_bf16(o[0], o[1]); w.y = cvt_pk_bf16(o[2], o[3]); w.z = cvt_pk_bf16(o[4], o[5]); w.w = cvt_pk_bf16(o[6], o[7]);
;                     bf16_t* dst;
;                     if (tile < 4) dst = P + (size_t)row * PP + C_DQ + tile * BM + bj * HALF + cc;
;                     else if (tile < 8) dst = KD + ((size_t)((b * 8 + (tile - 4) * 2 + bj) * SEQ + t)) * 128 + cc;
;                     else if (tile < 12) dst = P + (size_t)row * PP + C_SQ + (tile - 8) * BM + bj * HALF + cc;
;                     else if (tile == 12) { const int ccf = bj * HALF + cc; dst = KS + ((size_t)((b * 4 + (ccf >> 6)) * SEQ + t)) * 64 + (ccf & 63); }
;                     else dst = P + (size_t)row * PP + C_GA + (tile - 13) * BM + bj * HALF + cc;
;                     *(u32x4*)dst = w;
	v_fmamk_f32 v65, v224, 0x3a800000, v170
	v_rsq_f32_e32 v65, v65
	s_mov_b64 s[94:95], -1
	s_and_b64 vcc, exec, s[14:15]
	v_mul_f32_e32 v65, v153, v65
	v_mul_f32_e32 v75, v60, v65
	v_fma_f32 v60, v60, v65, v187
	v_mul_f32_e32 v60, 0xbfb8aa3b, v60
	v_exp_f32_e32 v60, v60
	s_nop 0
	v_add_f32_e32 v60, 1.0, v60
	v_rcp_f32_e32 v60, v60
	s_nop 0
	v_cndmask_b32_e64 v60, v75, v60, s[10:11]
	v_mul_f32_e32 v75, v61, v65
	v_fma_f32 v61, v61, v65, v186
	v_mul_f32_e32 v61, 0xbfb8aa3b, v61
	v_exp_f32_e32 v61, v61
	s_nop 0
	v_add_f32_e32 v61, 1.0, v61
	v_rcp_f32_e32 v61, v61
	s_nop 0
	v_cndmask_b32_e64 v61, v75, v61, s[10:11]
	v_mul_f32_e32 v75, v62, v65
	v_fma_f32 v62, v62, v65, v191
	v_mul_f32_e32 v62, 0xbfb8aa3b, v62
	v_exp_f32_e32 v62, v62
	s_nop 0
	v_add_f32_e32 v62, 1.0, v62
	v_rcp_f32_e32 v62, v62
	s_nop 0
	v_cndmask_b32_e64 v62, v75, v62, s[10:11]
	v_mul_f32_e32 v75, v63, v65
	v_fma_f32 v63, v63, v65, v188
	v_mul_f32_e32 v63, 0xbfb8aa3b, v63
	v_exp_f32_e32 v63, v63
	s_nop 0
	v_add_f32_e32 v63, 1.0, v63
	v_rcp_f32_e32 v63, v63
	s_nop 0
	v_cndmask_b32_e64 v63, v75, v63, s[10:11]
	v_mul_f32_e32 v75, v56, v65
	v_fma_f32 v56, v56, v65, v192
	v_mul_f32_e32 v56, 0xbfb8aa3b, v56
	v_exp_f32_e32 v56, v56
	s_nop 0
	v_add_f32_e32 v56, 1.0, v56
	v_rcp_f32_e32 v56, v56
	s_nop 0
	v_cndmask_b32_e64 v75, v75, v56, s[10:11]
	v_mul_f32_e32 v56, v57, v65
	v_fma_f32 v57, v57, v65, v189
	v_mul_f32_e32 v57, 0xbfb8aa3b, v57
	v_exp_f32_e32 v57, v57
	s_nop 0
	v_add_f32_e32 v57, 1.0, v57
	v_rcp_f32_e32 v57, v57
	s_nop 0
	v_cndmask_b32_e64 v76, v56, v57, s[10:11]
	v_fma_f32 v57, v58, v65, v193
	v_mul_f32_e32 v57, 0xbfb8aa3b, v57
	v_exp_f32_e32 v57, v57
	v_mul_f32_e32 v56, v58, v65
	v_cvt_pk_bf16_f32 v58, v75, v76
	v_add_f32_e32 v57, 1.0, v57
	v_rcp_f32_e32 v57, v57
	s_nop 0
	v_cndmask_b32_e64 v77, v56, v57, s[10:11]
	v_fma_f32 v57, v59, v65, v190
	v_mul_f32_e32 v57, 0xbfb8aa3b, v57
	v_exp_f32_e32 v57, v57
	v_mul_f32_e32 v56, v59, v65
	v_add_f32_e32 v57, 1.0, v57
	v_rcp_f32_e32 v57, v57
	s_nop 0
	v_cndmask_b32_e64 v59, v56, v57, s[10:11]
	v_cvt_pk_bf16_f32 v56, v60, v61
	v_cvt_pk_bf16_f32 v57, v62, v63
	v_cvt_pk_bf16_f32 v59, v77, v59
	global_store_dwordx4 v[70:71], v[56:59], off nt
	s_cbranch_vccnz .LBB0_592
	s_and_b64 vcc, exec, s[12:13]
	s_mov_b64 s[6:7], -1
	s_cbranch_vccnz .LBB0_589
	s_andn2_b64 vcc, exec, s[90:91]
	s_cbranch_vccnz .LBB0_586
	s_andn2_b64 vcc, exec, s[88:89]
	s_cbranch_vccnz .LBB0_583
	v_lshl_add_u64 v[56:57], s[0:1], 1, v[68:69]
	v_lshl_add_u64 v[56:57], v[56:57], 0, v[136:137]
	v_lshl_add_u64 v[56:57], v[56:57], 0, s[36:37]
	s_mov_b64 s[6:7], 0

; __device__ __forceinline__ unsigned cvt_pk_bf16(float lo, float hi) { f32x2_t v = {lo, hi}; bf16x2_t b = __builtin_convertvector(v, bf16x2_t); return __builtin_bit_cast(unsigned, b); }
; __device__ __forceinline__ float sigmoidf_(float v) { return __builtin_amdgcn_rcpf(1.0f + __builtin_amdgcn_exp2f(-v * LOG2E)); }
;     __device__ __forceinline__ void operator()(const Acc& acc, const Unit& u, int wr, int wc, int fr, int fq) const {
;     ...
;                 const int b = row >> 11, t = row & (SEQ - 1);
; #pragma unroll
;                 for (int bj = 0; bj < 2; ++bj) {
;                     float o[8];
; #pragma unroll
;                     for (int n = 0; n < 2; ++n)
; #pragma unroll
;                         for (int e = 0; e < 4; ++e) { float v = acc[ai][bj][m][n][e] * rs; if (isg) v = sigmoidf_(v + bv[bj][4 * n + e]); o[4 * n + e] = v; }
;                     u32x4 w; w.x = cvt_pk_bf16(o[0], o[1]); w.y = cvt_pk_bf16(o[2], o[3]); w.z = cvt_pk_bf16(o[4], o[5]); w.w = cvt_pk_bf16(o[6], o[7]);
;                     bf16_t* dst;
;                     if (tile < 4) dst = P + (size_t)row * PP + C_DQ + tile * BM + bj * HALF + cc;
;                     else if (tile < 8) dst = KD + ((size_t)((b * 8 + (tile - 4) * 2 + bj) * SEQ + t)) * 128 + cc;
;                     else if (tile < 12) dst = P + (size_t)row * PP + C_SQ + (tile - 8) * BM + bj * HALF + cc;
;                     else if (tile == 12) { const int ccf = bj * HALF + cc; dst = KS + ((size_t)((b * 4 + (ccf >> 6)) * SEQ + t)) * 64 + (ccf & 63); }
;                     else dst = P + (size_t)row * PP + C_GA + (tile - 13) * BM + bj * HALF + cc;
;                     *(u32x4*)dst = w;
.LBB0_594:
	v_mul_f32_e32 v58, v52, v65
	v_fma_f32 v52, v52, v65, v181
	v_mul_f32_e32 v52, 0xbfb8aa3b, v52
	v_exp_f32_e32 v52, v52
	s_mov_b64 s[94:95], -1
	s_and_b64 vcc, exec, s[14:15]
	v_add_f32_e32 v52, 1.0, v52
	v_rcp_f32_e32 v52, v52
	s_nop 0
	v_cndmask_b32_e64 v52, v58, v52, s[10:11]
	v_mul_f32_e32 v58, v53, v65
	v_fma_f32 v53, v53, v65, v174
	v_mul_f32_e32 v53, 0xbfb8aa3b, v53
	v_exp_f32_e32 v53, v53
	s_nop 0
	v_add_f32_e32 v53, 1.0, v53
	v_rcp_f32_e32 v53, v53
	s_nop 0
	v_cndmask_b32_e64 v53, v58, v53, s[10:11]
	v_mul_f32_e32 v58, v54, v65
	v_fma_f32 v54, v54, v65, v183
	v_mul_f32_e32 v54, 0xbfb8aa3b, v54
	v_exp_f32_e32 v54, v54
	s_nop 0
	v_add_f32_e32 v54, 1.0, v54
	v_rcp_f32_e32 v54, v54
	s_nop 0
	v_cndmask_b32_e64 v54, v58, v54, s[10:11]
	v_mul_f32_e32 v58, v55, v65
	v_fma_f32 v55, v55, v65, v178
	v_mul_f32_e32 v55, 0xbfb8aa3b, v55
	v_exp_f32_e32 v55, v55
	s_nop 0
	v_add_f32_e32 v55, 1.0, v55
	v_rcp_f32_e32 v55, v55
	s_nop 0
	v_cndmask_b32_e64 v55, v58, v55, s[10:11]
	v_mul_f32_e32 v58, v48, v65
	v_fma_f32 v48, v48, v65, v184
	v_mul_f32_e32 v48, 0xbfb8aa3b, v48
	v_exp_f32_e32 v48, v48
	s_nop 0
	v_add_f32_e32 v48, 1.0, v48
	v_rcp_f32_e32 v48, v48
	s_nop 0
	v_cndmask_b32_e64 v58, v58, v48, s[10:11]
	v_mul_f32_e32 v48, v49, v65
	v_fma_f32 v49, v49, v65, v180
	v_mul_f32_e32 v49, 0xbfb8aa3b, v49
	v_exp_f32_e32 v49, v49
	s_nop 0
	v_add_f32_e32 v49, 1.0, v49
	v_rcp_f32_e32 v49, v49
	s_nop 0
	v_cndmask_b32_e64 v59, v48, v49, s[10:11]
	v_fma_f32 v49, v50, v65, v185
	v_mul_f32_e32 v49, 0xbfb8aa3b, v49
	v_exp_f32_e32 v49, v49
	v_mul_f32_e32 v48, v50, v65
	v_cvt_pk_bf16_f32 v50, v58, v59
	v_add_f32_e32 v49, 1.0, v49
	v_rcp_f32_e32 v49, v49
	s_nop 0
	v_cndmask_b32_e64 v60, v48, v49, s[10:11]
	v_fma_f32 v49, v51, v65, v182
	v_mul_f32_e32 v49, 0xbfb8aa3b, v49
	v_exp_f32_e32 v49, v49
	v_mul_f32_e32 v48, v51, v65
	v_add_f32_e32 v49, 1.0, v49
	v_rcp_f32_e32 v49, v49
	s_nop 0
	v_cndmask_b32_e64 v51, v48, v49, s[10:11]
	v_cvt_pk_bf16_f32 v48, v52, v53
	v_cvt_pk_bf16_f32 v49, v54, v55
	v_cvt_pk_bf16_f32 v51, v60, v51
	global_store_dwordx4 v[56:57], v[48:51], off nt
	s_nop 0
	s_nop 0
	v_add_u32_e32 v48, 0x90, v152
	v_ashrrev_i32_e32 v49, 31, v48
	v_and_b32_e32 v56, 0x7df, v48
	v_lshlrev_b64 v[50:51], 13, v[48:49]
	v_or_b32_e32 v48, v73, v56
	s_cbranch_vccnz .LBB0_608
	s_and_b64 vcc, exec, s[12:13]
	s_mov_b64 s[6:7], -1
	s_cbranch_vccnz .LBB0_605
	s_andn2_b64 vcc, exec, s[90:91]
	s_cbranch_vccnz .LBB0_602
	s_andn2_b64 vcc, exec, s[88:89]
	s_cbranch_vccnz .LBB0_599
	v_lshl_add_u64 v[52:53], s[20:21], 0, v[50:51]
	v_lshl_add_u64 v[52:53], s[0:1], 1, v[52:53]
	v_lshl_add_u64 v[52:53], v[52:53], 0, v[136:137]
	v_lshl_add_u64 v[54:55], v[52:53], 0, s[30:31]
	s_mov_b64 s[6:7], 0

;     __device__ __forceinline__ void operator()(const Acc& acc, const Unit& u, int wr, int wc, int fr, int fq) const {
;     ...
;                     bf16_t* dst;
;                     if (tile < 4) dst = P + (size_t)row * PP + C_DQ + tile * BM + bj * HALF + cc;
;                     else if (tile < 8) dst = KD + ((size_t)((b * 8 + (tile - 4) * 2 + bj) * SEQ + t)) * 128 + cc;
;                     else if (tile < 12) dst = P + (size_t)row * PP + C_SQ + (tile - 8) * BM + bj * HALF + cc;
;                     else if (tile == 12) { const int ccf = bj * HALF + cc; dst = KS + ((size_t)((b * 4 + (ccf >> 6)) * SEQ + t)) * 64 + (ccf & 63); }
;                     else dst = P + (size_t)row * PP + C_GA + (tile - 13) * BM + bj * HALF + cc;
;                     *(u32x4*)dst = w;
.LBB0_610:

; __device__ __forceinline__ unsigned cvt_pk_bf16(float lo, float hi) { f32x2_t v = {lo, hi}; bf16x2_t b = __builtin_convertvector(v, bf16x2_t); return __builtin_bit_cast(unsigned, b); }
; __device__ __forceinline__ float rstd_of(const float* ss, int row) { return __builtin_amdgcn_rsqf(ss[row] * (1.0f / 1024.0f) + RMS_EPS); }
; __device__ __forceinline__ float sigmoidf_(float v) { return __builtin_amdgcn_rcpf(1.0f + __builtin_amdgcn_exp2f(-v * LOG2E)); }
;     __device__ __forceinline__ void operator()(const Acc& acc, const Unit& u, int wr, int wc, int fr, int fq) const {
;     ...
;                 const int row = row0 + ai * HALF + m * 16; const float rs = rstd_of(ss, row) * sc;
;                 const int b = row >> 11, t = row & (SEQ - 1);
; #pragma unroll
;                 for (int bj = 0; bj < 2; ++bj) {
;                     float o[8];
; #pragma unroll
;                     for (int n = 0; n < 2; ++n)
; #pragma unroll
;                         for (int e = 0; e < 4; ++e) { float v = acc[ai][bj][m][n][e] * rs; if (isg) v = sigmoidf_(v + bv[bj][4 * n + e]); o[4 * n + e] = v; }
;                     u32x4 w; w.x = cvt_pk_bf16(o[0], o[1]); w.y = cvt_pk_bf16(o[2], o[3]); w.z = cvt_pk_bf16(o[4], o[5]); w.w = cvt_pk_bf16(o[6], o[7]);
;                     bf16_t* dst;
;                     if (tile < 4) dst = P + (size_t)row * PP + C_DQ + tile * BM + bj * HALF + cc;
;                     else if (tile < 8) dst = KD + ((size_t)((b * 8 + (tile - 4) * 2 + bj) * SEQ + t)) * 128 + cc;
;                     else if (tile < 12) dst = P + (size_t)row * PP + C_SQ + (tile - 8) * BM + bj * HALF + cc;
;                     else if (tile == 12) { const int ccf = bj * HALF + cc; dst = KS + ((size_t)((b * 4 + (ccf >> 6)) * SEQ + t)) * 64 + (ccf & 63); }
;                     else dst = P + (size_t)row * PP + C_GA + (tile - 13) * BM + bj * HALF + cc;
;                     *(u32x4*)dst = w;
	v_fmamk_f32 v49, v225, 0x3a800000, v170
	v_rsq_f32_e32 v49, v49
	s_mov_b64 s[94:95], -1
	s_and_b64 vcc, exec, s[14:15]
	v_mul_f32_e32 v49, v153, v49
	v_mul_f32_e32 v57, v44, v49
	v_fma_f32 v44, v44, v49, v187
	v_mul_f32_e32 v44, 0xbfb8aa3b, v44
	v_exp_f32_e32 v44, v44
	s_nop 0
	v_add_f32_e32 v44, 1.0, v44
	v_rcp_f32_e32 v44, v44
	s_nop 0
	v_cndmask_b32_e64 v44, v57, v44, s[10:11]
	v_mul_f32_e32 v57, v45, v49
	v_fma_f32 v45, v45, v49, v186
	v_mul_f32_e32 v45, 0xbfb8aa3b, v45
	v_exp_f32_e32 v45, v45
	s_nop 0
	v_add_f32_e32 v45, 1.0, v45
	v_rcp_f32_e32 v45, v45
	s_nop 0
	v_cndmask_b32_e64 v45, v57, v45, s[10:11]
	v_mul_f32_e32 v57, v46, v49
	v_fma_f32 v46, v46, v49, v191
	v_mul_f32_e32 v46, 0xbfb8aa3b, v46
	v_exp_f32_e32 v46, v46
	s_nop 0
	v_add_f32_e32 v46, 1.0, v46
	v_rcp_f32_e32 v46, v46
	s_nop 0
	v_cndmask_b32_e64 v46, v57, v46, s[10:11]
	v_mul_f32_e32 v57, v47, v49
	v_fma_f32 v47, v47, v49, v188
	v_mul_f32_e32 v47, 0xbfb8aa3b, v47
	v_exp_f32_e32 v47, v47
	s_nop 0
	v_add_f32_e32 v47, 1.0, v47
	v_rcp_f32_e32 v47, v47
	s_nop 0
	v_cndmask_b32_e64 v47, v57, v47, s[10:11]
	v_mul_f32_e32 v57, v40, v49
	v_fma_f32 v40, v40, v49, v192
	v_mul_f32_e32 v40, 0xbfb8aa3b, v40
	v_exp_f32_e32 v40, v40
	s_nop 0
	v_add_f32_e32 v40, 1.0, v40
	v_rcp_f32_e32 v40, v40
	s_nop 0
	v_cndmask_b32_e64 v57, v57, v40, s[10:11]
	v_mul_f32_e32 v40, v41, v49
	v_fma_f32 v41, v41, v49, v189
	v_mul_f32_e32 v41, 0xbfb8aa3b, v41
	v_exp_f32_e32 v41, v41
	s_nop 0
	v_add_f32_e32 v41, 1.0, v41
	v_rcp_f32_e32 v41, v41
	s_nop 0
	v_cndmask_b32_e64 v58, v40, v41, s[10:11]
	v_fma_f32 v41, v42, v49, v193
	v_mul_f32_e32 v41, 0xbfb8aa3b, v41
	v_exp_f32_e32 v41, v41
	v_mul_f32_e32 v40, v42, v49
	v_cvt_pk_bf16_f32 v42, v57, v58
	v_add_f32_e32 v41, 1.0, v41
	v_rcp_f32_e32 v41, v41
	s_nop 0
	v_cndmask_b32_e64 v59, v40, v41, s[10:11]
	v_fma_f32 v41, v43, v49, v190
	v_mul_f32_e32 v41, 0xbfb8aa3b, v41
	v_exp_f32_e32 v41, v41
	v_mul_f32_e32 v40, v43, v49
	v_add_f32_e32 v41, 1.0, v41
	v_rcp_f32_e32 v41, v41
	s_nop 0
	v_cndmask_b32_e64 v43, v40, v41, s[10:11]
	v_cvt_pk_bf16_f32 v40, v44, v45
	v_cvt_pk_bf16_f32 v41, v46, v47
	v_cvt_pk_bf16_f32 v43, v59, v43
	global_store_dwordx4 v[54:55], v[40:43], off nt
	s_cbranch_vccnz .LBB0_624
	s_and_b64 vcc, exec, s[12:13]
	s_mov_b64 s[6:7], -1
	s_cbranch_vccnz .LBB0_621
	s_andn2_b64 vcc, exec, s[90:91]
	s_cbranch_vccnz .LBB0_618
	s_andn2_b64 vcc, exec, s[88:89]
	s_cbranch_vccnz .LBB0_615
	v_lshl_add_u64 v[40:41], s[0:1], 1, v[52:53]
	v_lshl_add_u64 v[40:41], v[40:41], 0, v[136:137]
	v_lshl_add_u64 v[40:41], v[40:41], 0, s[36:37]
	s_mov_b64 s[6:7], 0

; __device__ __forceinline__ unsigned cvt_pk_bf16(float lo, float hi) { f32x2_t v = {lo, hi}; bf16x2_t b = __builtin_convertvector(v, bf16x2_t); return __builtin_bit_cast(unsigned, b); }
; __device__ __forceinline__ float sigmoidf_(float v) { return __builtin_amdgcn_rcpf(1.0f + __builtin_amdgcn_exp2f(-v * LOG2E)); }
;     __device__ __forceinline__ void operator()(const Acc& acc, const Unit& u, int wr, int wc, int fr, int fq) const {
;     ...
;                 const int b = row >> 11, t = row & (SEQ - 1);
; #pragma unroll
;                 for (int bj = 0; bj < 2; ++bj) {
;                     float o[8];
; #pragma unroll
;                     for (int n = 0; n < 2; ++n)
; #pragma unroll
;                         for (int e = 0; e < 4; ++e) { float v = acc[ai][bj][m][n][e] * rs; if (isg) v = sigmoidf_(v + bv[bj][4 * n + e]); o[4 * n + e] = v; }
;                     u32x4 w; w.x = cvt_pk_bf16(o[0], o[1]); w.y = cvt_pk_bf16(o[2], o[3]); w.z = cvt_pk_bf16(o[4], o[5]); w.w = cvt_pk_bf16(o[6], o[7]);
;                     bf16_t* dst;
;                     if (tile < 4) dst = P + (size_t)row * PP + C_DQ + tile * BM + bj * HALF + cc;
;                     else if (tile < 8) dst = KD + ((size_t)((b * 8 + (tile - 4) * 2 + bj) * SEQ + t)) * 128 + cc;
;                     else if (tile < 12) dst = P + (size_t)row * PP + C_SQ + (tile - 8) * BM + bj * HALF + cc;
;                     else if (tile == 12) { const int ccf = bj * HALF + cc; dst = KS + ((size_t)((b * 4 + (ccf >> 6)) * SEQ + t)) * 64 + (ccf & 63); }
;                     else dst = P + (size_t)row * PP + C_GA + (tile - 13) * BM + bj * HALF + cc;
;                     *(u32x4*)dst = w;
.LBB0_626:
	v_mul_f32_e32 v42, v36, v49
	v_fma_f32 v36, v36, v49, v181
	v_mul_f32_e32 v36, 0xbfb8aa3b, v36
	v_exp_f32_e32 v36, v36
	s_mov_b64 s[94:95], -1
	s_and_b64 vcc, exec, s[14:15]
	v_add_f32_e32 v36, 1.0, v36
	v_rcp_f32_e32 v36, v36
	s_nop 0
	v_cndmask_b32_e64 v36, v42, v36, s[10:11]
	v_mul_f32_e32 v42, v37, v49
	v_fma_f32 v37, v37, v49, v174
	v_mul_f32_e32 v37, 0xbfb8aa3b, v37
	v_exp_f32_e32 v37, v37
	s_nop 0
	v_add_f32_e32 v37, 1.0, v37
	v_rcp_f32_e32 v37, v37
	s_nop 0
	v_cndmask_b32_e64 v37, v42, v37, s[10:11]
	v_mul_f32_e32 v42, v38, v49
	v_fma_f32 v38, v38, v49, v183
	v_mul_f32_e32 v38, 0xbfb8aa3b, v38
	v_exp_f32_e32 v38, v38
	s_nop 0
	v_add_f32_e32 v38, 1.0, v38
	v_rcp_f32_e32 v38, v38
	s_nop 0
	v_cndmask_b32_e64 v38, v42, v38, s[10:11]
	v_mul_f32_e32 v42, v39, v49
	v_fma_f32 v39, v39, v49, v178
	v_mul_f32_e32 v39, 0xbfb8aa3b, v39
	v_exp_f32_e32 v39, v39
	s_nop 0
	v_add_f32_e32 v39, 1.0, v39
	v_rcp_f32_e32 v39, v39
	s_nop 0
	v_cndmask_b32_e64 v39, v42, v39, s[10:11]
	v_mul_f32_e32 v42, v32, v49
	v_fma_f32 v32, v32, v49, v184
	v_mul_f32_e32 v32, 0xbfb8aa3b, v32
	v_exp_f32_e32 v32, v32
	s_nop 0
	v_add_f32_e32 v32, 1.0, v32
	v_rcp_f32_e32 v32, v32
	s_nop 0
	v_cndmask_b32_e64 v42, v42, v32, s[10:11]
	v_mul_f32_e32 v32, v33, v49
	v_fma_f32 v33, v33, v49, v180
	v_mul_f32_e32 v33, 0xbfb8aa3b, v33
	v_exp_f32_e32 v33, v33
	s_nop 0
	v_add_f32_e32 v33, 1.0, v33
	v_rcp_f32_e32 v33, v33
	s_nop 0
	v_cndmask_b32_e64 v43, v32, v33, s[10:11]
	v_fma_f32 v33, v34, v49, v185
	v_mul_f32_e32 v33, 0xbfb8aa3b, v33
	v_exp_f32_e32 v33, v33
	v_mul_f32_e32 v32, v34, v49
	v_cvt_pk_bf16_f32 v34, v42, v43
	v_add_f32_e32 v33, 1.0, v33
	v_rcp_f32_e32 v33, v33
	s_nop 0
	v_cndmask_b32_e64 v44, v32, v33, s[10:11]
	v_fma_f32 v33, v35, v49, v182
	v_mul_f32_e32 v33, 0xbfb8aa3b, v33
	v_exp_f32_e32 v33, v33
	v_mul_f32_e32 v32, v35, v49
	v_add_f32_e32 v33, 1.0, v33
	v_rcp_f32_e32 v33, v33
	s_nop 0
	v_cndmask_b32_e64 v35, v32, v33, s[10:11]
	v_cvt_pk_bf16_f32 v32, v36, v37
	v_cvt_pk_bf16_f32 v33, v38, v39
	v_cvt_pk_bf16_f32 v35, v44, v35
	global_store_dwordx4 v[40:41], v[32:35], off nt
	s_nop 0
	s_nop 0
	v_add_u32_e32 v32, 0xa0, v152
	v_ashrrev_i32_e32 v33, 31, v32
	v_and_b32_e32 v40, 0x7ef, v32
	v_lshlrev_b64 v[34:35], 13, v[32:33]
	v_or_b32_e32 v32, v73, v40
	s_cbranch_vccnz .LBB0_640
	s_and_b64 vcc, exec, s[12:13]
	s_mov_b64 s[6:7], -1
	s_cbranch_vccnz .LBB0_637
	s_andn2_b64 vcc, exec, s[90:91]
	s_cbranch_vccnz .LBB0_634
	s_andn2_b64 vcc, exec, s[88:89]
	s_cbranch_vccnz .LBB0_631
	v_lshl_add_u64 v[36:37], s[20:21], 0, v[34:35]
	v_lshl_add_u64 v[36:37], s[0:1], 1, v[36:37]
	v_lshl_add_u64 v[36:37], v[36:37], 0, v[136:137]
	v_lshl_add_u64 v[38:39], v[36:37], 0, s[30:31]
	s_mov_b64 s[6:7], 0

;     __device__ __forceinline__ void operator()(const Acc& acc, const Unit& u, int wr, int wc, int fr, int fq) const {
;     ...
;                     bf16_t* dst;
;                     if (tile < 4) dst = P + (size_t)row * PP + C_DQ + tile * BM + bj * HALF + cc;
;                     else if (tile < 8) dst = KD + ((size_t)((b * 8 + (tile - 4) * 2 + bj) * SEQ + t)) * 128 + cc;
;                     else if (tile < 12) dst = P + (size_t)row * PP + C_SQ + (tile - 8) * BM + bj * HALF + cc;
;                     else if (tile == 12) { const int ccf = bj * HALF + cc; dst = KS + ((size_t)((b * 4 + (ccf >> 6)) * SEQ + t)) * 64 + (ccf & 63); }
;                     else dst = P + (size_t)row * PP + C_GA + (tile - 13) * BM + bj * HALF + cc;
;                     *(u32x4*)dst = w;
.LBB0_642:

; __device__ __forceinline__ unsigned cvt_pk_bf16(float lo, float hi) { f32x2_t v = {lo, hi}; bf16x2_t b = __builtin_convertvector(v, bf16x2_t); return __builtin_bit_cast(unsigned, b); }
; __device__ __forceinline__ float rstd_of(const float* ss, int row) { return __builtin_amdgcn_rsqf(ss[row] * (1.0f / 1024.0f) + RMS_EPS); }
; __device__ __forceinline__ float sigmoidf_(float v) { return __builtin_amdgcn_rcpf(1.0f + __builtin_amdgcn_exp2f(-v * LOG2E)); }
;     __device__ __forceinline__ void operator()(const Acc& acc, const Unit& u, int wr, int wc, int fr, int fq) const {
;     ...
;                 const int row = row0 + ai * HALF + m * 16; const float rs = rstd_of(ss, row) * sc;
;                 const int b = row >> 11, t = row & (SEQ - 1);
; #pragma unroll
;                 for (int bj = 0; bj < 2; ++bj) {
;                     float o[8];
; #pragma unroll
;                     for (int n = 0; n < 2; ++n)
; #pragma unroll
;                         for (int e = 0; e < 4; ++e) { float v = acc[ai][bj][m][n][e] * rs; if (isg) v = sigmoidf_(v + bv[bj][4 * n + e]); o[4 * n + e] = v; }
;                     u32x4 w; w.x = cvt_pk_bf16(o[0], o[1]); w.y = cvt_pk_bf16(o[2], o[3]); w.z = cvt_pk_bf16(o[4], o[5]); w.w = cvt_pk_bf16(o[6], o[7]);
;                     bf16_t* dst;
;                     if (tile < 4) dst = P + (size_t)row * PP + C_DQ + tile * BM + bj * HALF + cc;
;                     else if (tile < 8) dst = KD + ((size_t)((b * 8 + (tile - 4) * 2 + bj) * SEQ + t)) * 128 + cc;
;                     else if (tile < 12) dst = P + (size_t)row * PP + C_SQ + (tile - 8) * BM + bj * HALF + cc;
;                     else if (tile == 12) { const int ccf = bj * HALF + cc; dst = KS + ((size_t)((b * 4 + (ccf >> 6)) * SEQ + t)) * 64 + (ccf & 63); }
;                     else dst = P + (size_t)row * PP + C_GA + (tile - 13) * BM + bj * HALF + cc;
;                     *(u32x4*)dst = w;
	v_fmamk_f32 v33, v226, 0x3a800000, v170
	v_rsq_f32_e32 v33, v33
	s_mov_b64 s[94:95], -1
	s_and_b64 vcc, exec, s[14:15]
	v_mul_f32_e32 v33, v153, v33
	v_mul_f32_e32 v41, v28, v33
	v_fma_f32 v28, v28, v33, v187
	v_mul_f32_e32 v28, 0xbfb8aa3b, v28
	v_exp_f32_e32 v28, v28
	s_nop 0
	v_add_f32_e32 v28, 1.0, v28
	v_rcp_f32_e32 v28, v28
	s_nop 0
	v_cndmask_b32_e64 v28, v41, v28, s[10:11]
	v_mul_f32_e32 v41, v29, v33
	v_fma_f32 v29, v29, v33, v186
	v_mul_f32_e32 v29, 0xbfb8aa3b, v29
	v_exp_f32_e32 v29, v29
	s_nop 0
	v_add_f32_e32 v29, 1.0, v29
	v_rcp_f32_e32 v29, v29
	s_nop 0
	v_cndmask_b32_e64 v29, v41, v29, s[10:11]
	v_mul_f32_e32 v41, v30, v33
	v_fma_f32 v30, v30, v33, v191
	v_mul_f32_e32 v30, 0xbfb8aa3b, v30
	v_exp_f32_e32 v30, v30
	s_nop 0
	v_add_f32_e32 v30, 1.0, v30
	v_rcp_f32_e32 v30, v30
	s_nop 0
	v_cndmask_b32_e64 v30, v41, v30, s[10:11]
	v_mul_f32_e32 v41, v31, v33
	v_fma_f32 v31, v31, v33, v188
	v_mul_f32_e32 v31, 0xbfb8aa3b, v31
	v_exp_f32_e32 v31, v31
	s_nop 0
	v_add_f32_e32 v31, 1.0, v31
	v_rcp_f32_e32 v31, v31
	s_nop 0
	v_cndmask_b32_e64 v31, v41, v31, s[10:11]
	v_mul_f32_e32 v41, v24, v33
	v_fma_f32 v24, v24, v33, v192
	v_mul_f32_e32 v24, 0xbfb8aa3b, v24
	v_exp_f32_e32 v24, v24
	s_nop 0
	v_add_f32_e32 v24, 1.0, v24
	v_rcp_f32_e32 v24, v24
	s_nop 0
	v_cndmask_b32_e64 v41, v41, v24, s[10:11]
	v_mul_f32_e32 v24, v25, v33
	v_fma_f32 v25, v25, v33, v189
	v_mul_f32_e32 v25, 0xbfb8aa3b, v25
	v_exp_f32_e32 v25, v25
	s_nop 0
	v_add_f32_e32 v25, 1.0, v25
	v_rcp_f32_e32 v25, v25
	s_nop 0
	v_cndmask_b32_e64 v42, v24, v25, s[10:11]
	v_fma_f32 v25, v26, v33, v193
	v_mul_f32_e32 v25, 0xbfb8aa3b, v25
	v_exp_f32_e32 v25, v25
	v_mul_f32_e32 v24, v26, v33
	v_cvt_pk_bf16_f32 v26, v41, v42
	v_add_f32_e32 v25, 1.0, v25
	v_rcp_f32_e32 v25, v25
	s_nop 0
	v_cndmask_b32_e64 v43, v24, v25, s[10:11]
	v_fma_f32 v25, v27, v33, v190
	v_mul_f32_e32 v25, 0xbfb8aa3b, v25
	v_exp_f32_e32 v25, v25
	v_mul_f32_e32 v24, v27, v33
	v_add_f32_e32 v25, 1.0, v25
	v_rcp_f32_e32 v25, v25
	s_nop 0
	v_cndmask_b32_e64 v27, v24, v25, s[10:11]
	v_cvt_pk_bf16_f32 v24, v28, v29
	v_cvt_pk_bf16_f32 v25, v30, v31
	v_cvt_pk_bf16_f32 v27, v43, v27
	global_store_dwordx4 v[38:39], v[24:27], off nt
	s_cbranch_vccnz .LBB0_656
	s_and_b64 vcc, exec, s[12:13]
	s_mov_b64 s[6:7], -1
	s_cbranch_vccnz .LBB0_653
	s_andn2_b64 vcc, exec, s[90:91]
	s_cbranch_vccnz .LBB0_650
	s_andn2_b64 vcc, exec, s[88:89]
	s_cbranch_vccnz .LBB0_647
	v_lshl_add_u64 v[24:25], s[0:1], 1, v[36:37]
	v_lshl_add_u64 v[24:25], v[24:25], 0, v[136:137]
	v_lshl_add_u64 v[24:25], v[24:25], 0, s[36:37]
	s_mov_b64 s[6:7], 0

; __device__ __forceinline__ unsigned cvt_pk_bf16(float lo, float hi) { f32x2_t v = {lo, hi}; bf16x2_t b = __builtin_convertvector(v, bf16x2_t); return __builtin_bit_cast(unsigned, b); }
; __device__ __forceinline__ float sigmoidf_(float v) { return __builtin_amdgcn_rcpf(1.0f + __builtin_amdgcn_exp2f(-v * LOG2E)); }
;     __device__ __forceinline__ void operator()(const Acc& acc, const Unit& u, int wr, int wc, int fr, int fq) const {
;     ...
;                 const int b = row >> 11, t = row & (SEQ - 1);
; #pragma unroll
;                 for (int bj = 0; bj < 2; ++bj) {
;                     float o[8];
; #pragma unroll
;                     for (int n = 0; n < 2; ++n)
; #pragma unroll
;                         for (int e = 0; e < 4; ++e) { float v = acc[ai][bj][m][n][e] * rs; if (isg) v = sigmoidf_(v + bv[bj][4 * n + e]); o[4 * n + e] = v; }
;                     u32x4 w; w.x = cvt_pk_bf16(o[0], o[1]); w.y = cvt_pk_bf16(o[2], o[3]); w.z = cvt_pk_bf16(o[4], o[5]); w.w = cvt_pk_bf16(o[6], o[7]);
;                     bf16_t* dst;
;                     if (tile < 4) dst = P + (size_t)row * PP + C_DQ + tile * BM + bj * HALF + cc;
;                     else if (tile < 8) dst = KD + ((size_t)((b * 8 + (tile - 4) * 2 + bj) * SEQ + t)) * 128 + cc;
;                     else if (tile < 12) dst = P + (size_t)row * PP + C_SQ + (tile - 8) * BM + bj * HALF + cc;
;                     else if (tile == 12) { const int ccf = bj * HALF + cc; dst = KS + ((size_t)((b * 4 + (ccf >> 6)) * SEQ + t)) * 64 + (ccf & 63); }
;                     else dst = P + (size_t)row * PP + C_GA + (tile - 13) * BM + bj * HALF + cc;
;                     *(u32x4*)dst = w;
.LBB0_658:
	v_mul_f32_e32 v26, v20, v33
	v_fma_f32 v20, v20, v33, v181
	v_mul_f32_e32 v20, 0xbfb8aa3b, v20
	v_exp_f32_e32 v20, v20
	s_mov_b64 s[94:95], -1
	s_and_b64 vcc, exec, s[14:15]
	v_add_f32_e32 v20, 1.0, v20
	v_rcp_f32_e32 v20, v20
	s_nop 0
	v_cndmask_b32_e64 v20, v26, v20, s[10:11]
	v_mul_f32_e32 v26, v21, v33
	v_fma_f32 v21, v21, v33, v174
	v_mul_f32_e32 v21, 0xbfb8aa3b, v21
	v_exp_f32_e32 v21, v21
	s_nop 0
	v_add_f32_e32 v21, 1.0, v21
	v_rcp_f32_e32 v21, v21
	s_nop 0
	v_cndmask_b32_e64 v21, v26, v21, s[10:11]
	v_mul_f32_e32 v26, v22, v33
	v_fma_f32 v22, v22, v33, v183
	v_mul_f32_e32 v22, 0xbfb8aa3b, v22
	v_exp_f32_e32 v22, v22
	s_nop 0
	v_add_f32_e32 v22, 1.0, v22
	v_rcp_f32_e32 v22, v22
	s_nop 0
	v_cndmask_b32_e64 v22, v26, v22, s[10:11]
	v_mul_f32_e32 v26, v23, v33
	v_fma_f32 v23, v23, v33, v178
	v_mul_f32_e32 v23, 0xbfb8aa3b, v23
	v_exp_f32_e32 v23, v23
	s_nop 0
	v_add_f32_e32 v23, 1.0, v23
	v_rcp_f32_e32 v23, v23
	s_nop 0
	v_cndmask_b32_e64 v23, v26, v23, s[10:11]
	v_mul_f32_e32 v26, v16, v33
	v_fma_f32 v16, v16, v33, v184
	v_mul_f32_e32 v16, 0xbfb8aa3b, v16
	v_exp_f32_e32 v16, v16
	s_nop 0
	v_add_f32_e32 v16, 1.0, v16
	v_rcp_f32_e32 v16, v16
	s_nop 0
	v_cndmask_b32_e64 v26, v26, v16, s[10:11]
	v_mul_f32_e32 v16, v17, v33
	v_fma_f32 v17, v17, v33, v180
	v_mul_f32_e32 v17, 0xbfb8aa3b, v17
	v_exp_f32_e32 v17, v17
	s_nop 0
	v_add_f32_e32 v17, 1.0, v17
	v_rcp_f32_e32 v17, v17
	s_nop 0
	v_cndmask_b32_e64 v27, v16, v17, s[10:11]
	v_fma_f32 v17, v18, v33, v185
	v_mul_f32_e32 v17, 0xbfb8aa3b, v17
	v_exp_f32_e32 v17, v17
	v_mul_f32_e32 v16, v18, v33
	v_cvt_pk_bf16_f32 v18, v26, v27
	v_add_f32_e32 v17, 1.0, v17
	v_rcp_f32_e32 v17, v17
	s_nop 0
	v_cndmask_b32_e64 v28, v16, v17, s[10:11]
	v_fma_f32 v17, v19, v33, v182
	v_mul_f32_e32 v17, 0xbfb8aa3b, v17
	v_exp_f32_e32 v17, v17
	v_mul_f32_e32 v16, v19, v33
	v_add_f32_e32 v17, 1.0, v17
	v_rcp_f32_e32 v17, v17
	s_nop 0
	v_cndmask_b32_e64 v19, v16, v17, s[10:11]
	v_cvt_pk_bf16_f32 v16, v20, v21
	v_cvt_pk_bf16_f32 v17, v22, v23
	v_cvt_pk_bf16_f32 v19, v28, v19
	global_store_dwordx4 v[24:25], v[16:19], off nt
	s_nop 0
	s_nop 0
	v_add_u32_e32 v16, 0xb0, v152
	v_ashrrev_i32_e32 v17, 31, v16
	v_and_b32_e32 v24, 0x7ff, v16
	v_lshlrev_b64 v[18:19], 13, v[16:17]
	v_or_b32_e32 v16, v73, v24
	s_cbranch_vccnz .LBB0_672
	s_and_b64 vcc, exec, s[12:13]
	s_mov_b64 s[6:7], -1
	s_cbranch_vccnz .LBB0_669
	s_andn2_b64 vcc, exec, s[90:91]
	s_cbranch_vccnz .LBB0_666
	s_andn2_b64 vcc, exec, s[88:89]
	s_cbranch_vccnz .LBB0_663
	v_lshl_add_u64 v[20:21], s[20:21], 0, v[18:19]
	v_lshl_add_u64 v[20:21], s[0:1], 1, v[20:21]
	v_lshl_add_u64 v[20:21], v[20:21], 0, v[136:137]
	v_lshl_add_u64 v[22:23], v[20:21], 0, s[30:31]
	s_mov_b64 s[6:7], 0

;     __device__ __forceinline__ void operator()(const Acc& acc, const Unit& u, int wr, int wc, int fr, int fq) const {
;     ...
;                     bf16_t* dst;
;                     if (tile < 4) dst = P + (size_t)row * PP + C_DQ + tile * BM + bj * HALF + cc;
;                     else if (tile < 8) dst = KD + ((size_t)((b * 8 + (tile - 4) * 2 + bj) * SEQ + t)) * 128 + cc;
;                     else if (tile < 12) dst = P + (size_t)row * PP + C_SQ + (tile - 8) * BM + bj * HALF + cc;
;                     else if (tile == 12) { const int ccf = bj * HALF + cc; dst = KS + ((size_t)((b * 4 + (ccf >> 6)) * SEQ + t)) * 64 + (ccf & 63); }
;                     else dst = P + (size_t)row * PP + C_GA + (tile - 13) * BM + bj * HALF + cc;
;                     *(u32x4*)dst = w;
.LBB0_674:

; __device__ __forceinline__ unsigned cvt_pk_bf16(float lo, float hi) { f32x2_t v = {lo, hi}; bf16x2_t b = __builtin_convertvector(v, bf16x2_t); return __builtin_bit_cast(unsigned, b); }
; __device__ __forceinline__ float rstd_of(const float* ss, int row) { return __builtin_amdgcn_rsqf(ss[row] * (1.0f / 1024.0f) + RMS_EPS); }
; __device__ __forceinline__ float sigmoidf_(float v) { return __builtin_amdgcn_rcpf(1.0f + __builtin_amdgcn_exp2f(-v * LOG2E)); }
;     __device__ __forceinline__ void operator()(const Acc& acc, const Unit& u, int wr, int wc, int fr, int fq) const {
;     ...
;                 const int row = row0 + ai * HALF + m * 16; const float rs = rstd_of(ss, row) * sc;
;                 const int b = row >> 11, t = row & (SEQ - 1);
; #pragma unroll
;                 for (int bj = 0; bj < 2; ++bj) {
;                     float o[8];
; #pragma unroll
;                     for (int n = 0; n < 2; ++n)
; #pragma unroll
;                         for (int e = 0; e < 4; ++e) { float v = acc[ai][bj][m][n][e] * rs; if (isg) v = sigmoidf_(v + bv[bj][4 * n + e]); o[4 * n + e] = v; }
;                     u32x4 w; w.x = cvt_pk_bf16(o[0], o[1]); w.y = cvt_pk_bf16(o[2], o[3]); w.z = cvt_pk_bf16(o[4], o[5]); w.w = cvt_pk_bf16(o[6], o[7]);
;                     bf16_t* dst;
;                     if (tile < 4) dst = P + (size_t)row * PP + C_DQ + tile * BM + bj * HALF + cc;
;                     else if (tile < 8) dst = KD + ((size_t)((b * 8 + (tile - 4) * 2 + bj) * SEQ + t)) * 128 + cc;
;                     else if (tile < 12) dst = P + (size_t)row * PP + C_SQ + (tile - 8) * BM + bj * HALF + cc;
;                     else if (tile == 12) { const int ccf = bj * HALF + cc; dst = KS + ((size_t)((b * 4 + (ccf >> 6)) * SEQ + t)) * 64 + (ccf & 63); }
;                     else dst = P + (size_t)row * PP + C_GA + (tile - 13) * BM + bj * HALF + cc;
;                     *(u32x4*)dst = w;
	v_fmamk_f32 v17, v227, 0x3a800000, v170
	v_rsq_f32_e32 v17, v17
	s_and_b64 vcc, exec, s[14:15]
	s_mov_b64 s[6:7], -1
	v_mul_f32_e32 v17, v153, v17
	v_fmac_f32_e32 v187, v12, v17
	v_fmac_f32_e32 v186, v13, v17
	v_mul_f32_e32 v25, 0xbfb8aa3b, v187
	v_mul_f32_e32 v26, 0xbfb8aa3b, v186
	v_exp_f32_e32 v25, v25
	v_exp_f32_e32 v26, v26
	v_mul_f32_e32 v12, v12, v17
	v_mul_f32_e32 v13, v13, v17
	v_add_f32_e32 v25, 1.0, v25
	v_add_f32_e32 v26, 1.0, v26
	v_rcp_f32_e32 v25, v25
	v_rcp_f32_e32 v26, v26
	v_fmac_f32_e32 v191, v14, v17
	v_fmac_f32_e32 v188, v15, v17
	v_cndmask_b32_e64 v12, v12, v25, s[10:11]
	v_cndmask_b32_e64 v13, v13, v26, s[10:11]
	v_mul_f32_e32 v25, 0xbfb8aa3b, v191
	v_mul_f32_e32 v26, 0xbfb8aa3b, v188
	v_exp_f32_e32 v25, v25
	v_exp_f32_e32 v26, v26
	v_fmac_f32_e32 v192, v8, v17
	v_mul_f32_e32 v27, 0xbfb8aa3b, v192
	v_add_f32_e32 v25, 1.0, v25
	v_add_f32_e32 v26, 1.0, v26
	v_rcp_f32_e32 v25, v25
	v_rcp_f32_e32 v26, v26
	v_exp_f32_e32 v27, v27
	v_mul_f32_e32 v14, v14, v17
	v_mul_f32_e32 v15, v15, v17
	v_fmac_f32_e32 v189, v9, v17
	v_cndmask_b32_e64 v14, v14, v25, s[10:11]
	v_cndmask_b32_e64 v15, v15, v26, s[10:11]
	v_add_f32_e32 v25, 1.0, v27
	v_mul_f32_e32 v26, 0xbfb8aa3b, v189
	v_rcp_f32_e32 v25, v25
	v_exp_f32_e32 v26, v26
	v_mul_f32_e32 v8, v8, v17
	v_fmac_f32_e32 v193, v10, v17
	v_cndmask_b32_e64 v25, v8, v25, s[10:11]
	v_mul_f32_e32 v8, v9, v17
	v_add_f32_e32 v9, 1.0, v26
	v_mul_f32_e32 v26, 0xbfb8aa3b, v193
	v_fmac_f32_e32 v190, v11, v17
	v_rcp_f32_e32 v9, v9
	v_exp_f32_e32 v26, v26
	v_mul_f32_e32 v27, 0xbfb8aa3b, v190
	v_exp_f32_e32 v27, v27
	v_cndmask_b32_e64 v28, v8, v9, s[10:11]
	v_add_f32_e32 v8, 1.0, v26
	v_rcp_f32_e32 v8, v8
	v_add_f32_e32 v9, 1.0, v27
	v_rcp_f32_e32 v9, v9
	v_mul_f32_e32 v10, v10, v17
	v_cndmask_b32_e64 v26, v10, v8, s[10:11]
	v_mul_f32_e32 v8, v11, v17
	v_cndmask_b32_e64 v11, v8, v9, s[10:11]
	v_cvt_pk_bf16_f32 v8, v12, v13
	v_cvt_pk_bf16_f32 v9, v14, v15
	v_cvt_pk_bf16_f32 v10, v25, v28
	v_cvt_pk_bf16_f32 v11, v26, v11
	global_store_dwordx4 v[22:23], v[8:11], off nt
	s_cbranch_vccnz .LBB0_688
	s_and_b64 vcc, exec, s[12:13]
	s_cbranch_vccnz .LBB0_685
	s_andn2_b64 vcc, exec, s[90:91]
	s_cbranch_vccnz .LBB0_682
	s_andn2_b64 vcc, exec, s[88:89]
	s_cbranch_vccnz .LBB0_679
	v_lshl_add_u64 v[8:9], s[0:1], 1, v[20:21]
	v_lshl_add_u64 v[8:9], v[8:9], 0, v[136:137]
	v_lshl_add_u64 v[8:9], v[8:9], 0, s[36:37]
	s_mov_b64 s[6:7], 0
